# v29 + nt hint on P0 weight-conversion stores
# baseline (speedup 1.0000x reference)
; #define LAS __attribute__((address_space(3)))
; __device__ __forceinline__ unsigned f2bf(float f) { unsigned u = __builtin_bit_cast(unsigned, f); return (u + 0x7fffu + ((u >> 16) & 1u)) >> 16; }
; __device__ __forceinline__ unsigned pk2(float lo, float hi) { return f2bf(lo) | (f2bf(hi) << 16); }
; __device__ __forceinline__ void transpose_item(const float* W, int K, int N, int mode, const float* kscale, bf16_t* d0, bf16_t* d1, LAS float* scr, int item, int lane) {
;     ...
;     const int c = lane & 7;
; #pragma unroll
;     for (int j = 0; j < 4; ++j) { const int n = (lane >> 3) + 8 * j; const LAS float* s = scr + (8 * c) * 33 + n;
;         if (n0 + n < N) { float cs; bf16_t* dst = tmap(mode, n0 + n, d0, d1, K, cs);
;             u32x4 o; o.x = pk2(s[0 * 33] * cs, s[1 * 33] * cs); o.y = pk2(s[2 * 33] * cs, s[3 * 33] * cs); o.z = pk2(s[4 * 33] * cs, s[5 * 33] * cs); o.w = pk2(s[6 * 33] * cs, s[7 * 33] * cs);
;             *(u32x4*)(dst + k0 + 8 * c) = o; } }
.LBB0_19:
	s_or_b64 exec, exec, s[64:65]
	ds_read2_b32 v[4:5], v40 offset0:24 offset1:57
	ds_read2_b32 v[10:11], v40 offset0:90 offset1:123
	ds_read2_b32 v[12:13], v40 offset0:156 offset1:189
	ds_read2_b32 v[14:15], v40 offset0:222 offset1:255
	v_lshlrev_b64 v[6:7], 12, v[6:7]
	v_lshl_add_u64 v[8:9], v[8:9], 0, v[6:7]
	s_waitcnt lgkmcnt(0)
	v_mov_b32_e32 v6, v4
	v_mov_b32_e32 v7, v10
	v_mov_b32_e32 v10, v5
	v_pk_mul_f32 v[4:5], v[2:3], v[10:11] op_sel_hi:[0,1]
	v_mov_b32_e32 v11, v14
	v_mov_b32_e32 v14, v13
	v_mov_b32_e32 v10, v12
	v_pk_mul_f32 v[12:13], v[2:3], v[14:15] op_sel_hi:[0,1]
	v_pk_mul_f32 v[6:7], v[2:3], v[6:7] op_sel_hi:[0,1]
	v_pk_mul_f32 v[10:11], v[2:3], v[10:11] op_sel_hi:[0,1]
	v_bfe_u32 v14, v12, 16, 1
	v_bfe_u32 v16, v4, 16, 1
	v_bfe_u32 v2, v13, 16, 1
	v_bfe_u32 v15, v5, 16, 1
	v_add3_u32 v4, v4, v16, s85
	v_add3_u32 v12, v12, v14, s85
	v_bfe_u32 v14, v7, 16, 1
	v_bfe_u32 v16, v11, 16, 1
	v_add3_u32 v5, v5, v15, s85
	v_add3_u32 v2, v13, v2, s85
	v_bfe_u32 v13, v6, 16, 1
	v_bfe_u32 v15, v10, 16, 1
	v_add3_u32 v11, v11, v16, s85
	v_add3_u32 v7, v7, v14, s85
	v_add3_u32 v10, v10, v15, s85
	v_add3_u32 v6, v6, v13, s85
	v_lshrrev_b32_e32 v14, 16, v7
	v_lshrrev_b32_e32 v7, 16, v11
	v_lshrrev_b32_e32 v13, 16, v6
	v_lshrrev_b32_e32 v6, 16, v10
	v_and_or_b32 v7, v2, s86, v7
	v_lshl_add_u64 v[8:9], s[4:5], 1, v[8:9]
	v_lshlrev_b32_e32 v2, 1, v0
	v_and_or_b32 v6, v12, s86, v6
	v_and_or_b32 v5, v5, s86, v14
	v_and_or_b32 v4, v4, s86, v13
	v_lshl_add_u64 v[8:9], v[8:9], 0, v[2:3]
	flat_store_dwordx4 v[8:9], v[4:7] nt

; #define LAS __attribute__((address_space(3)))
; __device__ __forceinline__ unsigned f2bf(float f) { unsigned u = __builtin_bit_cast(unsigned, f); return (u + 0x7fffu + ((u >> 16) & 1u)) >> 16; }
; __device__ __forceinline__ unsigned pk2(float lo, float hi) { return f2bf(lo) | (f2bf(hi) << 16); }
; __device__ __forceinline__ void transpose_item(const float* W, int K, int N, int mode, const float* kscale, bf16_t* d0, bf16_t* d1, LAS float* scr, int item, int lane) {
;     ...
; #pragma unroll
;     for (int i = 0; i < 32; ++i) { const int kk = 2 * i + (lane >> 5); scr[kk * 33 + (lane & 31)] = tv[i]; }
;     asm volatile("s_waitcnt lgkmcnt(0)" ::: "memory");
;     const int c = lane & 7;
; #pragma unroll
;     for (int j = 0; j < 4; ++j) { const int n = (lane >> 3) + 8 * j; const LAS float* s = scr + (8 * c) * 33 + n;
;         if (n0 + n < N) { float cs; bf16_t* dst = tmap(mode, n0 + n, d0, d1, K, cs);
;             u32x4 o; o.x = pk2(s[0 * 33] * cs, s[1 * 33] * cs); o.y = pk2(s[2 * 33] * cs, s[3 * 33] * cs); o.z = pk2(s[4 * 33] * cs, s[5 * 33] * cs); o.w = pk2(s[6 * 33] * cs, s[7 * 33] * cs);
;             *(u32x4*)(dst + k0 + 8 * c) = o; } }
.LBB0_93:
	s_or_b64 exec, exec, s[62:63]
	v_add_u32_e32 v2, 0x400, v38
	s_waitcnt vmcnt(0)
	ds_write2_b32 v38, v6, v7 offset1:66
	ds_write2_b32 v38, v9, v8 offset0:132 offset1:198
	ds_write2_b32 v2, v11, v10 offset0:8 offset1:74
	ds_write2_b32 v2, v13, v12 offset0:140 offset1:206
	v_add_u32_e32 v2, 0x800, v38
	ds_write2_b32 v2, v15, v14 offset0:16 offset1:82
	ds_write2_b32 v2, v17, v16 offset0:148 offset1:214
	v_add_u32_e32 v2, 0xc00, v38
	ds_write2_b32 v2, v19, v18 offset0:24 offset1:90
	ds_write2_b32 v2, v21, v20 offset0:156 offset1:222
	v_add_u32_e32 v2, 0x1000, v38
	ds_write2_b32 v2, v23, v22 offset0:32 offset1:98
	ds_write2_b32 v2, v25, v24 offset0:164 offset1:230
	v_add_u32_e32 v2, 0x1400, v38
	ds_write2_b32 v2, v27, v26 offset0:40 offset1:106
	ds_write2_b32 v2, v29, v28 offset0:172 offset1:238
	v_add_u32_e32 v2, 0x1800, v38
	ds_write2_b32 v2, v31, v30 offset0:48 offset1:114
	ds_write2_b32 v2, v33, v32 offset0:180 offset1:246
	v_add_u32_e32 v2, 0x1c00, v38
	s_sub_i32 s40, 0, s40
	ds_write2_b32 v2, v35, v34 offset0:56 offset1:122
	ds_write2_b32 v2, v37, v36 offset0:188 offset1:254
	s_waitcnt lgkmcnt(0)
	s_add_i32 s40, s40, s74
	v_add_u32_e32 v2, s40, v49
	v_cmp_gt_i32_e32 vcc, s83, v2
	s_and_saveexec_b64 s[4:5], vcc
	s_cbranch_execz .LBB0_95
	ds_read2_b32 v[4:5], v40 offset1:33
	ds_read2_b32 v[8:9], v40 offset0:66 offset1:99
	v_mov_b64_e32 v[6:7], s[38:39]
	v_mad_i64_i32 v[10:11], s[48:49], v2, s84, v[6:7]
	s_waitcnt lgkmcnt(1)
	v_bfe_u32 v2, v4, 16, 1
	v_add3_u32 v2, v4, v2, s85
	v_bfe_u32 v4, v5, 16, 1
	ds_read2_b32 v[6:7], v40 offset0:132 offset1:165
	v_lshrrev_b32_e32 v2, 16, v2
	v_add3_u32 v4, v5, v4, s85
	v_and_or_b32 v4, v4, s86, v2
	s_waitcnt lgkmcnt(1)
	v_bfe_u32 v2, v8, 16, 1
	v_bfe_u32 v5, v9, 16, 1
	v_add3_u32 v2, v8, v2, s85
	v_add3_u32 v5, v9, v5, s85
	ds_read2_b32 v[8:9], v40 offset0:198 offset1:231
	v_lshrrev_b32_e32 v2, 16, v2
	v_and_or_b32 v5, v5, s86, v2
	s_waitcnt lgkmcnt(1)
	v_bfe_u32 v2, v6, 16, 1
	v_add3_u32 v2, v6, v2, s85
	v_bfe_u32 v6, v7, 16, 1
	v_lshrrev_b32_e32 v2, 16, v2
	v_add3_u32 v6, v7, v6, s85
	v_and_or_b32 v6, v6, s86, v2
	s_waitcnt lgkmcnt(0)
	v_bfe_u32 v2, v8, 16, 1
	v_add3_u32 v2, v8, v2, s85
	v_bfe_u32 v7, v9, 16, 1
	v_lshrrev_b32_e32 v2, 16, v2
	v_add3_u32 v7, v9, v7, s85
	v_and_or_b32 v7, v7, s86, v2
	v_lshl_add_u64 v[8:9], s[42:43], 1, v[10:11]
	v_lshlrev_b32_e32 v2, 1, v0
	v_lshl_add_u64 v[8:9], v[8:9], 0, v[2:3]
	flat_store_dwordx4 v[8:9], v[4:7] nt
.LBB0_95:
	s_or_b64 exec, exec, s[4:5]
	v_add_u32_e32 v2, s40, v50
	v_cmp_gt_i32_e32 vcc, s83, v2
	s_and_saveexec_b64 s[4:5], vcc
	s_cbranch_execz .LBB0_97
	ds_read2_b32 v[4:5], v40 offset0:8 offset1:41
	ds_read2_b32 v[8:9], v40 offset0:74 offset1:107
	v_mov_b64_e32 v[6:7], s[38:39]
	v_mad_i64_i32 v[10:11], s[48:49], v2, s84, v[6:7]
	s_waitcnt lgkmcnt(0)
	v_bfe_u32 v2, v4, 16, 1
	v_add3_u32 v2, v4, v2, s85
	v_bfe_u32 v4, v5, 16, 1
	ds_read2_b32 v[6:7], v40 offset0:140 offset1:173
	v_lshrrev_b32_e32 v2, 16, v2
	v_add3_u32 v4, v5, v4, s85
	v_and_or_b32 v4, v4, s86, v2
	v_bfe_u32 v2, v8, 16, 1
	v_bfe_u32 v5, v9, 16, 1
	v_add3_u32 v2, v8, v2, s85
	v_add3_u32 v5, v9, v5, s85
	ds_read2_b32 v[8:9], v40 offset0:206 offset1:239
	v_lshrrev_b32_e32 v2, 16, v2
	v_and_or_b32 v5, v5, s86, v2
	s_waitcnt lgkmcnt(0)
	v_bfe_u32 v2, v6, 16, 1
	v_add3_u32 v2, v6, v2, s85
	v_bfe_u32 v6, v7, 16, 1
	v_lshrrev_b32_e32 v2, 16, v2
	v_add3_u32 v6, v7, v6, s85
	v_and_or_b32 v6, v6, s86, v2
	v_bfe_u32 v2, v8, 16, 1
	v_add3_u32 v2, v8, v2, s85
	v_bfe_u32 v7, v9, 16, 1
	v_lshrrev_b32_e32 v2, 16, v2
	v_add3_u32 v7, v9, v7, s85
	v_and_or_b32 v7, v7, s86, v2
	v_lshl_add_u64 v[8:9], s[42:43], 1, v[10:11]
	v_lshlrev_b32_e32 v2, 1, v0
	v_lshl_add_u64 v[8:9], v[8:9], 0, v[2:3]
	flat_store_dwordx4 v[8:9], v[4:7] nt
.LBB0_97:
	s_or_b64 exec, exec, s[4:5]
	v_add_u32_e32 v2, s40, v51
	v_cmp_gt_i32_e32 vcc, s83, v2
	s_and_saveexec_b64 s[4:5], vcc
	s_cbranch_execz .LBB0_99
	ds_read2_b32 v[4:5], v40 offset0:16 offset1:49
	ds_read2_b32 v[8:9], v40 offset0:82 offset1:115
	v_mov_b64_e32 v[6:7], s[38:39]
	v_mad_i64_i32 v[10:11], s[48:49], v2, s84, v[6:7]
	s_waitcnt lgkmcnt(0)
	v_bfe_u32 v2, v4, 16, 1
	v_add3_u32 v2, v4, v2, s85
	v_bfe_u32 v4, v5, 16, 1
	ds_read2_b32 v[6:7], v40 offset0:148 offset1:181
	v_lshrrev_b32_e32 v2, 16, v2
	v_add3_u32 v4, v5, v4, s85
	v_and_or_b32 v4, v4, s86, v2
	v_bfe_u32 v2, v8, 16, 1
	v_bfe_u32 v5, v9, 16, 1
	v_add3_u32 v2, v8, v2, s85
	v_add3_u32 v5, v9, v5, s85
	ds_read2_b32 v[8:9], v40 offset0:214 offset1:247
	v_lshrrev_b32_e32 v2, 16, v2
	v_and_or_b32 v5, v5, s86, v2
	s_waitcnt lgkmcnt(0)
	v_bfe_u32 v2, v6, 16, 1
	v_add3_u32 v2, v6, v2, s85
	v_bfe_u32 v6, v7, 16, 1
	v_lshrrev_b32_e32 v2, 16, v2
	v_add3_u32 v6, v7, v6, s85
	v_and_or_b32 v6, v6, s86, v2
	v_bfe_u32 v2, v8, 16, 1
	v_add3_u32 v2, v8, v2, s85
	v_bfe_u32 v7, v9, 16, 1
	v_lshrrev_b32_e32 v2, 16, v2
	v_add3_u32 v7, v9, v7, s85
	v_and_or_b32 v7, v7, s86, v2
	v_lshl_add_u64 v[8:9], s[42:43], 1, v[10:11]
	v_lshlrev_b32_e32 v2, 1, v0
	v_lshl_add_u64 v[8:9], v[8:9], 0, v[2:3]
	flat_store_dwordx4 v[8:9], v[4:7] nt
.LBB0_99:
	s_or_b64 exec, exec, s[4:5]
	v_add_u32_e32 v2, s40, v52
	v_cmp_gt_i32_e32 vcc, s83, v2
	s_and_saveexec_b64 s[4:5], vcc
	s_cbranch_execz .LBB0_101
	ds_read2_b32 v[4:5], v40 offset0:24 offset1:57
	ds_read2_b32 v[8:9], v40 offset0:90 offset1:123
	v_mov_b64_e32 v[6:7], s[38:39]
	v_mad_i64_i32 v[10:11], s[40:41], v2, s84, v[6:7]
	s_waitcnt lgkmcnt(0)
	v_bfe_u32 v2, v4, 16, 1
	v_add3_u32 v2, v4, v2, s85
	v_bfe_u32 v4, v5, 16, 1
	ds_read2_b32 v[6:7], v40 offset0:156 offset1:189
	v_lshrrev_b32_e32 v2, 16, v2
	v_add3_u32 v4, v5, v4, s85
	v_and_or_b32 v4, v4, s86, v2
	v_bfe_u32 v2, v8, 16, 1
	v_bfe_u32 v5, v9, 16, 1
	v_add3_u32 v2, v8, v2, s85
	v_add3_u32 v5, v9, v5, s85
	ds_read2_b32 v[8:9], v40 offset0:222 offset1:255
	v_lshrrev_b32_e32 v2, 16, v2
	v_and_or_b32 v5, v5, s86, v2
	s_waitcnt lgkmcnt(0)
	v_bfe_u32 v2, v6, 16, 1
	v_add3_u32 v2, v6, v2, s85
	v_bfe_u32 v6, v7, 16, 1
	v_lshrrev_b32_e32 v2, 16, v2
	v_add3_u32 v6, v7, v6, s85
	v_and_or_b32 v6, v6, s86, v2
	v_bfe_u32 v2, v8, 16, 1
	v_add3_u32 v2, v8, v2, s85
	v_bfe_u32 v7, v9, 16, 1
	v_lshrrev_b32_e32 v2, 16, v2
	v_add3_u32 v7, v9, v7, s85
	v_and_or_b32 v7, v7, s86, v2
	v_lshl_add_u64 v[8:9], s[42:43], 1, v[10:11]
	v_lshlrev_b32_e32 v2, 1, v0
	v_lshl_add_u64 v[8:9], v[8:9], 0, v[2:3]
	flat_store_dwordx4 v[8:9], v[4:7] nt

; #define LAS __attribute__((address_space(3)))
; __device__ __forceinline__ unsigned pk2(float lo, float hi) { return f2bf(lo) | (f2bf(hi) << 16); }
; __device__ __forceinline__ bf16_t* tmap(int mode, int n, bf16_t* d0, bf16_t* d1, int K, float& cs) {
;     ...
;     if (mode == 4) { const int g = (n >= DFF) ? 1 : 0, c = n - g * DFF; return d0 + (size_t)((c >> 7) * 256 + 64 * ((c & 127) >> 5) + 32 * g + (c & 31)) * K; }
; __device__ __forceinline__ void transpose_item(const float* W, int K, int N, int mode, const float* kscale, bf16_t* d0, bf16_t* d1, LAS float* scr, int item, int lane) {
;     ...
;     for (int i = 0; i < 32; ++i) { const int kk = 2 * i + (lane >> 5); scr[kk * 33 + (lane & 31)] = tv[i]; }
;     asm volatile("s_waitcnt lgkmcnt(0)" ::: "memory");
;     const int c = lane & 7;
; #pragma unroll
;     for (int j = 0; j < 4; ++j) { const int n = (lane >> 3) + 8 * j; const LAS float* s = scr + (8 * c) * 33 + n;
;         if (n0 + n < N) { float cs; bf16_t* dst = tmap(mode, n0 + n, d0, d1, K, cs);
;             u32x4 o; o.x = pk2(s[0 * 33] * cs, s[1 * 33] * cs); o.y = pk2(s[2 * 33] * cs, s[3 * 33] * cs); o.z = pk2(s[4 * 33] * cs, s[5 * 33] * cs); o.w = pk2(s[6 * 33] * cs, s[7 * 33] * cs);
;             *(u32x4*)(dst + k0 + 8 * c) = o; } }
.LBB0_167:
	s_or_b64 exec, exec, s[62:63]
	v_add_u32_e32 v2, 0x400, v38
	s_waitcnt vmcnt(0)
	ds_write2_b32 v38, v6, v7 offset1:66
	ds_write2_b32 v38, v9, v8 offset0:132 offset1:198
	ds_write2_b32 v2, v11, v10 offset0:8 offset1:74
	ds_write2_b32 v2, v13, v12 offset0:140 offset1:206
	v_add_u32_e32 v2, 0x800, v38
	ds_write2_b32 v2, v15, v14 offset0:16 offset1:82
	ds_write2_b32 v2, v17, v16 offset0:148 offset1:214
	v_add_u32_e32 v2, 0xc00, v38
	ds_write2_b32 v2, v19, v18 offset0:24 offset1:90
	ds_write2_b32 v2, v21, v20 offset0:156 offset1:222
	v_add_u32_e32 v2, 0x1000, v38
	ds_write2_b32 v2, v23, v22 offset0:32 offset1:98
	ds_write2_b32 v2, v25, v24 offset0:164 offset1:230
	v_add_u32_e32 v2, 0x1400, v38
	ds_write2_b32 v2, v27, v26 offset0:40 offset1:106
	ds_write2_b32 v2, v29, v28 offset0:172 offset1:238
	v_add_u32_e32 v2, 0x1800, v38
	ds_write2_b32 v2, v31, v30 offset0:48 offset1:114
	ds_write2_b32 v2, v33, v32 offset0:180 offset1:246
	v_add_u32_e32 v2, 0x1c00, v38
	ds_write2_b32 v2, v35, v34 offset0:56 offset1:122
	ds_write2_b32 v2, v37, v36 offset0:188 offset1:254
	s_waitcnt lgkmcnt(0)
	v_add_u32_e32 v2, s41, v56
	s_and_b32 s48, s76, 0xc0
	v_cmp_gt_i32_e32 vcc, s84, v2
	s_and_saveexec_b64 s[4:5], vcc
	s_cbranch_execz .LBB0_169
	v_cmp_lt_i32_e32 vcc, s87, v2
	ds_read2_b32 v[10:11], v40 offset0:132 offset1:165
	ds_read2_b32 v[12:13], v40 offset0:198 offset1:231
	v_cndmask_b32_e32 v2, 0, v78, vcc
	v_or_b32_e32 v2, v39, v2
	v_add_u32_e32 v2, s41, v2
	v_lshl_add_u32 v2, v2, 1, v79
	v_cndmask_b32_e64 v4, 0, 32, vcc
	v_and_or_b32 v2, v2, s88, v4
	ds_read2_b32 v[4:5], v40 offset1:33
	v_or3_b32 v6, v2, v39, s48
	v_ashrrev_i32_e32 v7, 31, v6
	v_lshlrev_b64 v[6:7], 12, v[6:7]
	v_lshl_add_u64 v[8:9], s[36:37], 0, v[6:7]
	ds_read2_b32 v[6:7], v40 offset0:66 offset1:99
	s_waitcnt lgkmcnt(1)
	v_bfe_u32 v2, v4, 16, 1
	v_add3_u32 v2, v4, v2, s85
	v_bfe_u32 v4, v5, 16, 1
	v_lshrrev_b32_e32 v2, 16, v2
	v_add3_u32 v4, v5, v4, s85
	v_and_or_b32 v4, v4, s86, v2
	s_waitcnt lgkmcnt(0)
	v_bfe_u32 v2, v6, 16, 1
	v_add3_u32 v2, v6, v2, s85
	v_bfe_u32 v5, v7, 16, 1
	v_lshrrev_b32_e32 v2, 16, v2
	v_add3_u32 v5, v7, v5, s85
	v_and_or_b32 v5, v5, s86, v2
	v_bfe_u32 v2, v10, 16, 1
	v_add3_u32 v2, v10, v2, s85
	v_bfe_u32 v6, v11, 16, 1
	v_lshrrev_b32_e32 v2, 16, v2
	v_add3_u32 v6, v11, v6, s85
	v_and_or_b32 v6, v6, s86, v2
	v_bfe_u32 v2, v12, 16, 1
	v_add3_u32 v2, v12, v2, s85
	v_bfe_u32 v7, v13, 16, 1
	v_lshrrev_b32_e32 v2, 16, v2
	v_add3_u32 v7, v13, v7, s85
	s_lshl_b32 s42, s40, 1
	v_and_or_b32 v7, v7, s86, v2
	v_lshl_add_u64 v[8:9], v[8:9], 0, s[42:43]
	v_lshlrev_b32_e32 v2, 1, v0
	v_lshl_add_u64 v[8:9], v[8:9], 0, v[2:3]
	flat_store_dwordx4 v[8:9], v[4:7] nt
.LBB0_169:
	s_or_b64 exec, exec, s[4:5]
	v_add_u32_e32 v2, s41, v55
	v_cmp_gt_i32_e32 vcc, s84, v2
	s_and_saveexec_b64 s[4:5], vcc
	s_cbranch_execz .LBB0_171
	v_cmp_lt_i32_e32 vcc, s87, v2
	ds_read2_b32 v[10:11], v40 offset0:140 offset1:173
	ds_read2_b32 v[12:13], v40 offset0:206 offset1:239
	v_cndmask_b32_e32 v2, 0, v78, vcc
	v_or_b32_e32 v2, v39, v2
	v_add_u32_e32 v2, s41, v2
	v_lshl_add_u32 v2, v2, 1, v80
	v_cndmask_b32_e64 v4, 0, 32, vcc
	v_and_or_b32 v2, v2, s88, v4
	ds_read2_b32 v[4:5], v40 offset0:8 offset1:41
	v_or3_b32 v6, v2, v41, s48
	v_ashrrev_i32_e32 v7, 31, v6
	v_lshlrev_b64 v[6:7], 12, v[6:7]
	v_lshl_add_u64 v[8:9], s[36:37], 0, v[6:7]
	ds_read2_b32 v[6:7], v40 offset0:74 offset1:107
	s_waitcnt lgkmcnt(0)
	v_bfe_u32 v2, v4, 16, 1
	v_add3_u32 v2, v4, v2, s85
	v_bfe_u32 v4, v5, 16, 1
	v_lshrrev_b32_e32 v2, 16, v2
	v_add3_u32 v4, v5, v4, s85
	v_and_or_b32 v4, v4, s86, v2
	v_bfe_u32 v2, v6, 16, 1
	v_add3_u32 v2, v6, v2, s85
	v_bfe_u32 v5, v7, 16, 1
	v_lshrrev_b32_e32 v2, 16, v2
	v_add3_u32 v5, v7, v5, s85
	v_and_or_b32 v5, v5, s86, v2
	v_bfe_u32 v2, v10, 16, 1
	v_add3_u32 v2, v10, v2, s85
	v_bfe_u32 v6, v11, 16, 1
	v_lshrrev_b32_e32 v2, 16, v2
	v_add3_u32 v6, v11, v6, s85
	v_and_or_b32 v6, v6, s86, v2
	v_bfe_u32 v2, v12, 16, 1
	v_add3_u32 v2, v12, v2, s85
	v_bfe_u32 v7, v13, 16, 1
	v_lshrrev_b32_e32 v2, 16, v2
	v_add3_u32 v7, v13, v7, s85
	s_lshl_b32 s42, s40, 1
	v_and_or_b32 v7, v7, s86, v2
	v_lshl_add_u64 v[8:9], v[8:9], 0, s[42:43]
	v_lshlrev_b32_e32 v2, 1, v0
	v_lshl_add_u64 v[8:9], v[8:9], 0, v[2:3]
	flat_store_dwordx4 v[8:9], v[4:7] nt
; #define LAS __attribute__((address_space(3)))
; __device__ __forceinline__ unsigned pk2(float lo, float hi) { return f2bf(lo) | (f2bf(hi) << 16); }
; __device__ __forceinline__ bf16_t* tmap(int mode, int n, bf16_t* d0, bf16_t* d1, int K, float& cs) {
;     ...
;     if (mode == 4) { const int g = (n >= DFF) ? 1 : 0, c = n - g * DFF; return d0 + (size_t)((c >> 7) * 256 + 64 * ((c & 127) >> 5) + 32 * g + (c & 31)) * K; }
; __device__ __forceinline__ void transpose_item(const float* W, int K, int N, int mode, const float* kscale, bf16_t* d0, bf16_t* d1, LAS float* scr, int item, int lane) {
;     ...
;     const int c = lane & 7;
; #pragma unroll
;     for (int j = 0; j < 4; ++j) { const int n = (lane >> 3) + 8 * j; const LAS float* s = scr + (8 * c) * 33 + n;
;         if (n0 + n < N) { float cs; bf16_t* dst = tmap(mode, n0 + n, d0, d1, K, cs);
;             u32x4 o; o.x = pk2(s[0 * 33] * cs, s[1 * 33] * cs); o.y = pk2(s[2 * 33] * cs, s[3 * 33] * cs); o.z = pk2(s[4 * 33] * cs, s[5 * 33] * cs); o.w = pk2(s[6 * 33] * cs, s[7 * 33] * cs);
;             *(u32x4*)(dst + k0 + 8 * c) = o; } }
.LBB0_171:
	s_or_b64 exec, exec, s[4:5]
	v_add_u32_e32 v2, s41, v54
	v_cmp_gt_i32_e32 vcc, s84, v2
	s_and_saveexec_b64 s[4:5], vcc
	s_cbranch_execz .LBB0_173
	v_cmp_lt_i32_e32 vcc, s87, v2
	ds_read2_b32 v[10:11], v40 offset0:148 offset1:181
	ds_read2_b32 v[12:13], v40 offset0:214 offset1:247
	v_cndmask_b32_e32 v2, 0, v78, vcc
	v_or_b32_e32 v2, v39, v2
	v_add_u32_e32 v2, s41, v2
	v_lshl_add_u32 v2, v2, 1, v81
	v_cndmask_b32_e64 v4, 0, 32, vcc
	v_and_or_b32 v2, v2, s88, v4
	ds_read2_b32 v[4:5], v40 offset0:16 offset1:49
	v_or3_b32 v6, v2, v42, s48
	v_ashrrev_i32_e32 v7, 31, v6
	v_lshlrev_b64 v[6:7], 12, v[6:7]
	v_lshl_add_u64 v[8:9], s[36:37], 0, v[6:7]
	ds_read2_b32 v[6:7], v40 offset0:82 offset1:115
	s_waitcnt lgkmcnt(0)
	v_bfe_u32 v2, v4, 16, 1
	v_add3_u32 v2, v4, v2, s85
	v_bfe_u32 v4, v5, 16, 1
	v_lshrrev_b32_e32 v2, 16, v2
	v_add3_u32 v4, v5, v4, s85
	v_and_or_b32 v4, v4, s86, v2
	v_bfe_u32 v2, v6, 16, 1
	v_add3_u32 v2, v6, v2, s85
	v_bfe_u32 v5, v7, 16, 1
	v_lshrrev_b32_e32 v2, 16, v2
	v_add3_u32 v5, v7, v5, s85
	v_and_or_b32 v5, v5, s86, v2
	v_bfe_u32 v2, v10, 16, 1
	v_add3_u32 v2, v10, v2, s85
	v_bfe_u32 v6, v11, 16, 1
	v_lshrrev_b32_e32 v2, 16, v2
	v_add3_u32 v6, v11, v6, s85
	v_and_or_b32 v6, v6, s86, v2
	v_bfe_u32 v2, v12, 16, 1
	v_add3_u32 v2, v12, v2, s85
	v_bfe_u32 v7, v13, 16, 1
	v_lshrrev_b32_e32 v2, 16, v2
	v_add3_u32 v7, v13, v7, s85
	s_lshl_b32 s42, s40, 1
	v_and_or_b32 v7, v7, s86, v2
	v_lshl_add_u64 v[8:9], v[8:9], 0, s[42:43]
	v_lshlrev_b32_e32 v2, 1, v0
	v_lshl_add_u64 v[8:9], v[8:9], 0, v[2:3]
	flat_store_dwordx4 v[8:9], v[4:7] nt
.LBB0_173:
	s_or_b64 exec, exec, s[4:5]
	v_add_u32_e32 v2, s41, v53
	v_cmp_gt_i32_e32 vcc, s84, v2
	s_and_saveexec_b64 s[4:5], vcc
	s_cbranch_execz .LBB0_175
	v_cmp_lt_i32_e32 vcc, s87, v2
	ds_read2_b32 v[10:11], v40 offset0:156 offset1:189
	ds_read2_b32 v[12:13], v40 offset0:222 offset1:255
	v_cndmask_b32_e32 v2, 0, v78, vcc
	v_or_b32_e32 v2, v39, v2
	v_add_u32_e32 v2, s41, v2
	v_lshl_add_u32 v2, v2, 1, v82
	v_cndmask_b32_e64 v4, 0, 32, vcc
	v_and_or_b32 v2, v2, s88, v4
	ds_read2_b32 v[4:5], v40 offset0:24 offset1:57
	v_or3_b32 v6, v2, v43, s48
	v_ashrrev_i32_e32 v7, 31, v6
	v_lshlrev_b64 v[6:7], 12, v[6:7]
	v_lshl_add_u64 v[8:9], s[36:37], 0, v[6:7]
	ds_read2_b32 v[6:7], v40 offset0:90 offset1:123
	s_waitcnt lgkmcnt(0)
	v_bfe_u32 v2, v4, 16, 1
	v_add3_u32 v2, v4, v2, s85
	v_bfe_u32 v4, v5, 16, 1
	v_lshrrev_b32_e32 v2, 16, v2
	v_add3_u32 v4, v5, v4, s85
	v_and_or_b32 v4, v4, s86, v2
	v_bfe_u32 v2, v6, 16, 1
	v_add3_u32 v2, v6, v2, s85
	v_bfe_u32 v5, v7, 16, 1
	v_lshrrev_b32_e32 v2, 16, v2
	v_add3_u32 v5, v7, v5, s85
	v_and_or_b32 v5, v5, s86, v2
	v_bfe_u32 v2, v10, 16, 1
	v_add3_u32 v2, v10, v2, s85
	v_bfe_u32 v6, v11, 16, 1
	v_lshrrev_b32_e32 v2, 16, v2
	v_add3_u32 v6, v11, v6, s85
	v_and_or_b32 v6, v6, s86, v2
	v_bfe_u32 v2, v12, 16, 1
	v_add3_u32 v2, v12, v2, s85
	v_bfe_u32 v7, v13, 16, 1
	v_lshrrev_b32_e32 v2, 16, v2
	v_add3_u32 v7, v13, v7, s85
	s_lshl_b32 s42, s40, 1
	v_and_or_b32 v7, v7, s86, v2
	v_lshl_add_u64 v[8:9], v[8:9], 0, s[42:43]
	v_lshlrev_b32_e32 v2, 1, v0
	v_lshl_add_u64 v[8:9], v[8:9], 0, v[2:3]
	flat_store_dwordx4 v[8:9], v[4:7] nt

; #define LAS __attribute__((address_space(3)))
; __device__ __forceinline__ unsigned pk2(float lo, float hi) { return f2bf(lo) | (f2bf(hi) << 16); }
; __device__ __forceinline__ bf16_t* tmap(int mode, int n, bf16_t* d0, bf16_t* d1, int K, float& cs) {
;     ...
;     if (mode == 0) return d0 + (size_t)n * K;
; __device__ __forceinline__ void transpose_item(const float* W, int K, int N, int mode, const float* kscale, bf16_t* d0, bf16_t* d1, LAS float* scr, int item, int lane) {
;     ...
; #pragma unroll
;     for (int i = 0; i < 32; ++i) { const int kk = 2 * i + (lane >> 5); scr[kk * 33 + (lane & 31)] = tv[i]; }
;     asm volatile("s_waitcnt lgkmcnt(0)" ::: "memory");
;     const int c = lane & 7;
; #pragma unroll
;     for (int j = 0; j < 4; ++j) { const int n = (lane >> 3) + 8 * j; const LAS float* s = scr + (8 * c) * 33 + n;
;         if (n0 + n < N) { float cs; bf16_t* dst = tmap(mode, n0 + n, d0, d1, K, cs);
;             u32x4 o; o.x = pk2(s[0 * 33] * cs, s[1 * 33] * cs); o.y = pk2(s[2 * 33] * cs, s[3 * 33] * cs); o.z = pk2(s[4 * 33] * cs, s[5 * 33] * cs); o.w = pk2(s[6 * 33] * cs, s[7 * 33] * cs);
;             *(u32x4*)(dst + k0 + 8 * c) = o; } }
.LBB0_241:
	s_or_b64 exec, exec, s[62:63]
	v_add_u32_e32 v2, 0x400, v38
	s_waitcnt vmcnt(0)
	ds_write2_b32 v38, v6, v7 offset1:66
	ds_write2_b32 v38, v9, v8 offset0:132 offset1:198
	ds_write2_b32 v2, v11, v10 offset0:8 offset1:74
	ds_write2_b32 v2, v13, v12 offset0:140 offset1:206
	v_add_u32_e32 v2, 0x800, v38
	ds_write2_b32 v2, v15, v14 offset0:16 offset1:82
	ds_write2_b32 v2, v17, v16 offset0:148 offset1:214
	v_add_u32_e32 v2, 0xc00, v38
	ds_write2_b32 v2, v19, v18 offset0:24 offset1:90
	ds_write2_b32 v2, v21, v20 offset0:156 offset1:222
	v_add_u32_e32 v2, 0x1000, v38
	ds_write2_b32 v2, v23, v22 offset0:32 offset1:98
	ds_write2_b32 v2, v25, v24 offset0:164 offset1:230
	v_add_u32_e32 v2, 0x1400, v38
	ds_write2_b32 v2, v27, v26 offset0:40 offset1:106
	ds_write2_b32 v2, v29, v28 offset0:172 offset1:238
	v_add_u32_e32 v2, 0x1800, v38
	ds_write2_b32 v2, v31, v30 offset0:48 offset1:114
	ds_write2_b32 v2, v33, v32 offset0:180 offset1:246
	v_add_u32_e32 v2, 0x1c00, v38
	s_sub_i32 s40, 0, s40
	ds_write2_b32 v2, v35, v34 offset0:56 offset1:122
	ds_write2_b32 v2, v37, v36 offset0:188 offset1:254
	s_waitcnt lgkmcnt(0)
	s_add_i32 s40, s40, s74
	v_add_u32_e32 v4, s40, v59
	v_cmp_gt_i32_e32 vcc, s83, v4
	s_and_saveexec_b64 s[4:5], vcc
	s_cbranch_execz .LBB0_243
	ds_read2_b32 v[6:7], v40 offset1:33
	v_ashrrev_i32_e32 v5, 31, v4
	ds_read2_b32 v[8:9], v40 offset0:66 offset1:99
	v_lshlrev_b64 v[4:5], 12, v[4:5]
	v_lshl_add_u64 v[10:11], s[34:35], 0, v[4:5]
	s_waitcnt lgkmcnt(1)
	v_bfe_u32 v2, v6, 16, 1
	v_bfe_u32 v4, v7, 16, 1
	v_add3_u32 v2, v6, v2, s85
	v_add3_u32 v4, v7, v4, s85
	ds_read2_b32 v[6:7], v40 offset0:132 offset1:165
	v_lshrrev_b32_e32 v2, 16, v2
	v_and_or_b32 v4, v4, s86, v2
	s_waitcnt lgkmcnt(1)
	v_bfe_u32 v2, v8, 16, 1
	v_bfe_u32 v5, v9, 16, 1
	v_add3_u32 v2, v8, v2, s85
	v_add3_u32 v5, v9, v5, s85
	ds_read2_b32 v[8:9], v40 offset0:198 offset1:231
	v_lshrrev_b32_e32 v2, 16, v2
	v_and_or_b32 v5, v5, s86, v2
	s_waitcnt lgkmcnt(1)
	v_bfe_u32 v2, v6, 16, 1
	v_add3_u32 v2, v6, v2, s85
	v_bfe_u32 v6, v7, 16, 1
	v_lshrrev_b32_e32 v2, 16, v2
	v_add3_u32 v6, v7, v6, s85
	v_and_or_b32 v6, v6, s86, v2
	s_waitcnt lgkmcnt(0)
	v_bfe_u32 v2, v8, 16, 1
	v_add3_u32 v2, v8, v2, s85
	v_bfe_u32 v7, v9, 16, 1
	v_lshrrev_b32_e32 v2, 16, v2
	v_add3_u32 v7, v9, v7, s85
	v_and_or_b32 v7, v7, s86, v2
	v_lshl_add_u64 v[8:9], s[42:43], 1, v[10:11]
	v_lshlrev_b32_e32 v2, 1, v0
	v_lshl_add_u64 v[8:9], v[8:9], 0, v[2:3]
	flat_store_dwordx4 v[8:9], v[4:7] nt
.LBB0_243:
	s_or_b64 exec, exec, s[4:5]
	s_nop 0
	v_add_u32_e32 v4, s40, v60
	v_cmp_gt_i32_e32 vcc, s83, v4
	s_and_saveexec_b64 s[4:5], vcc
	s_cbranch_execz .LBB0_245
	ds_read2_b32 v[6:7], v40 offset0:8 offset1:41
	v_ashrrev_i32_e32 v5, 31, v4
	ds_read2_b32 v[8:9], v40 offset0:74 offset1:107
	v_lshlrev_b64 v[4:5], 12, v[4:5]
	v_lshl_add_u64 v[10:11], s[34:35], 0, v[4:5]
	s_waitcnt lgkmcnt(0)
	v_bfe_u32 v2, v6, 16, 1
	v_bfe_u32 v4, v7, 16, 1
	v_add3_u32 v2, v6, v2, s85
	v_add3_u32 v4, v7, v4, s85
	ds_read2_b32 v[6:7], v40 offset0:140 offset1:173
	v_lshrrev_b32_e32 v2, 16, v2
	v_and_or_b32 v4, v4, s86, v2
	v_bfe_u32 v2, v8, 16, 1
	v_bfe_u32 v5, v9, 16, 1
	v_add3_u32 v2, v8, v2, s85
	v_add3_u32 v5, v9, v5, s85
	ds_read2_b32 v[8:9], v40 offset0:206 offset1:239
	v_lshrrev_b32_e32 v2, 16, v2
	v_and_or_b32 v5, v5, s86, v2
	s_waitcnt lgkmcnt(0)
	v_bfe_u32 v2, v6, 16, 1
	v_add3_u32 v2, v6, v2, s85
	v_bfe_u32 v6, v7, 16, 1
	v_lshrrev_b32_e32 v2, 16, v2
	v_add3_u32 v6, v7, v6, s85
	v_and_or_b32 v6, v6, s86, v2
	v_bfe_u32 v2, v8, 16, 1
	v_add3_u32 v2, v8, v2, s85
	v_bfe_u32 v7, v9, 16, 1
	v_lshrrev_b32_e32 v2, 16, v2
	v_add3_u32 v7, v9, v7, s85
	v_and_or_b32 v7, v7, s86, v2
	v_lshl_add_u64 v[8:9], s[42:43], 1, v[10:11]
	v_lshlrev_b32_e32 v2, 1, v0
	v_lshl_add_u64 v[8:9], v[8:9], 0, v[2:3]
	flat_store_dwordx4 v[8:9], v[4:7] nt
.LBB0_245:
	s_or_b64 exec, exec, s[4:5]
	s_nop 0
	v_add_u32_e32 v4, s40, v61
	v_cmp_gt_i32_e32 vcc, s83, v4
	s_and_saveexec_b64 s[4:5], vcc
	s_cbranch_execz .LBB0_247
	ds_read2_b32 v[6:7], v40 offset0:16 offset1:49
	v_ashrrev_i32_e32 v5, 31, v4
	ds_read2_b32 v[8:9], v40 offset0:82 offset1:115
	v_lshlrev_b64 v[4:5], 12, v[4:5]
	v_lshl_add_u64 v[10:11], s[34:35], 0, v[4:5]
	s_waitcnt lgkmcnt(0)
	v_bfe_u32 v2, v6, 16, 1
	v_bfe_u32 v4, v7, 16, 1
	v_add3_u32 v2, v6, v2, s85
	v_add3_u32 v4, v7, v4, s85
	ds_read2_b32 v[6:7], v40 offset0:148 offset1:181
	v_lshrrev_b32_e32 v2, 16, v2
	v_and_or_b32 v4, v4, s86, v2
	v_bfe_u32 v2, v8, 16, 1
	v_bfe_u32 v5, v9, 16, 1
	v_add3_u32 v2, v8, v2, s85
	v_add3_u32 v5, v9, v5, s85
	ds_read2_b32 v[8:9], v40 offset0:214 offset1:247
	v_lshrrev_b32_e32 v2, 16, v2
	v_and_or_b32 v5, v5, s86, v2
	s_waitcnt lgkmcnt(0)
	v_bfe_u32 v2, v6, 16, 1
	v_add3_u32 v2, v6, v2, s85
	v_bfe_u32 v6, v7, 16, 1
	v_lshrrev_b32_e32 v2, 16, v2
	v_add3_u32 v6, v7, v6, s85
	v_and_or_b32 v6, v6, s86, v2
	v_bfe_u32 v2, v8, 16, 1
	v_add3_u32 v2, v8, v2, s85
	v_bfe_u32 v7, v9, 16, 1
	v_lshrrev_b32_e32 v2, 16, v2
	v_add3_u32 v7, v9, v7, s85
	v_and_or_b32 v7, v7, s86, v2
	v_lshl_add_u64 v[8:9], s[42:43], 1, v[10:11]
	v_lshlrev_b32_e32 v2, 1, v0
	v_lshl_add_u64 v[8:9], v[8:9], 0, v[2:3]
	flat_store_dwordx4 v[8:9], v[4:7] nt
.LBB0_247:
	s_or_b64 exec, exec, s[4:5]
	s_nop 0
	v_add_u32_e32 v4, s40, v62
	v_cmp_gt_i32_e32 vcc, s83, v4
	s_and_saveexec_b64 s[4:5], vcc
	s_cbranch_execz .LBB0_249
	ds_read2_b32 v[6:7], v40 offset0:24 offset1:57
	v_ashrrev_i32_e32 v5, 31, v4
	ds_read2_b32 v[8:9], v40 offset0:90 offset1:123
	v_lshlrev_b64 v[4:5], 12, v[4:5]
	v_lshl_add_u64 v[10:11], s[34:35], 0, v[4:5]
	s_waitcnt lgkmcnt(0)
	v_bfe_u32 v2, v6, 16, 1
	v_bfe_u32 v4, v7, 16, 1
	v_add3_u32 v2, v6, v2, s85
	v_add3_u32 v4, v7, v4, s85
	ds_read2_b32 v[6:7], v40 offset0:156 offset1:189
	v_lshrrev_b32_e32 v2, 16, v2
	v_and_or_b32 v4, v4, s86, v2
	v_bfe_u32 v2, v8, 16, 1
	v_bfe_u32 v5, v9, 16, 1
	v_add3_u32 v2, v8, v2, s85
	v_add3_u32 v5, v9, v5, s85
	ds_read2_b32 v[8:9], v40 offset0:222 offset1:255
	v_lshrrev_b32_e32 v2, 16, v2
	v_and_or_b32 v5, v5, s86, v2
	s_waitcnt lgkmcnt(0)
	v_bfe_u32 v2, v6, 16, 1
	v_add3_u32 v2, v6, v2, s85
	v_bfe_u32 v6, v7, 16, 1
	v_lshrrev_b32_e32 v2, 16, v2
	v_add3_u32 v6, v7, v6, s85
	v_and_or_b32 v6, v6, s86, v2
	v_bfe_u32 v2, v8, 16, 1
	v_add3_u32 v2, v8, v2, s85
	v_bfe_u32 v7, v9, 16, 1
	v_lshrrev_b32_e32 v2, 16, v2
	v_add3_u32 v7, v9, v7, s85
	v_and_or_b32 v7, v7, s86, v2
	v_lshl_add_u64 v[8:9], s[42:43], 1, v[10:11]
	v_lshlrev_b32_e32 v2, 1, v0
	v_lshl_add_u64 v[8:9], v[8:9], 0, v[2:3]
	flat_store_dwordx4 v[8:9], v[4:7] nt

; #define LAS __attribute__((address_space(3)))
; __device__ __forceinline__ unsigned pk2(float lo, float hi) { return f2bf(lo) | (f2bf(hi) << 16); }
; __device__ __forceinline__ bf16_t* tmap(int mode, int n, bf16_t* d0, bf16_t* d1, int K, float& cs) {
;     ...
;     if (mode == 0) return d0 + (size_t)n * K;
; __device__ __forceinline__ void transpose_item(const float* W, int K, int N, int mode, const float* kscale, bf16_t* d0, bf16_t* d1, LAS float* scr, int item, int lane) {
;     ...
; #pragma unroll
;     for (int i = 0; i < 32; ++i) { const int kk = 2 * i + (lane >> 5); scr[kk * 33 + (lane & 31)] = tv[i]; }
;     asm volatile("s_waitcnt lgkmcnt(0)" ::: "memory");
;     const int c = lane & 7;
; #pragma unroll
;     for (int j = 0; j < 4; ++j) { const int n = (lane >> 3) + 8 * j; const LAS float* s = scr + (8 * c) * 33 + n;
;         if (n0 + n < N) { float cs; bf16_t* dst = tmap(mode, n0 + n, d0, d1, K, cs);
;             u32x4 o; o.x = pk2(s[0 * 33] * cs, s[1 * 33] * cs); o.y = pk2(s[2 * 33] * cs, s[3 * 33] * cs); o.z = pk2(s[4 * 33] * cs, s[5 * 33] * cs); o.w = pk2(s[6 * 33] * cs, s[7 * 33] * cs);
;             *(u32x4*)(dst + k0 + 8 * c) = o; } }
.LBB0_316:
	s_or_b64 exec, exec, s[62:63]
	v_add_u32_e32 v2, 0x400, v38
	s_waitcnt vmcnt(0)
	ds_write2_b32 v38, v6, v7 offset1:66
	ds_write2_b32 v38, v9, v8 offset0:132 offset1:198
	ds_write2_b32 v2, v11, v10 offset0:8 offset1:74
	ds_write2_b32 v2, v13, v12 offset0:140 offset1:206
	v_add_u32_e32 v2, 0x800, v38
	ds_write2_b32 v2, v15, v14 offset0:16 offset1:82
	ds_write2_b32 v2, v17, v16 offset0:148 offset1:214
	v_add_u32_e32 v2, 0xc00, v38
	ds_write2_b32 v2, v19, v18 offset0:24 offset1:90
	ds_write2_b32 v2, v21, v20 offset0:156 offset1:222
	v_add_u32_e32 v2, 0x1000, v38
	ds_write2_b32 v2, v23, v22 offset0:32 offset1:98
	ds_write2_b32 v2, v25, v24 offset0:164 offset1:230
	v_add_u32_e32 v2, 0x1400, v38
	ds_write2_b32 v2, v27, v26 offset0:40 offset1:106
	ds_write2_b32 v2, v29, v28 offset0:172 offset1:238
	v_add_u32_e32 v2, 0x1800, v38
	ds_write2_b32 v2, v31, v30 offset0:48 offset1:114
	ds_write2_b32 v2, v33, v32 offset0:180 offset1:246
	v_add_u32_e32 v2, 0x1c00, v38
	s_sub_i32 s40, 0, s40
	ds_write2_b32 v2, v35, v34 offset0:56 offset1:122
	ds_write2_b32 v2, v37, v36 offset0:188 offset1:254
	s_waitcnt lgkmcnt(0)
	s_add_i32 s40, s40, s74
	v_add_u32_e32 v4, s40, v64
	v_cmp_gt_i32_e32 vcc, s83, v4
	s_and_saveexec_b64 s[4:5], vcc
	s_cbranch_execz .LBB0_318
	ds_read2_b32 v[6:7], v40 offset1:33
	v_ashrrev_i32_e32 v5, 31, v4
	ds_read2_b32 v[8:9], v40 offset0:66 offset1:99
	v_lshlrev_b64 v[4:5], 11, v[4:5]
	v_lshl_add_u64 v[10:11], s[30:31], 0, v[4:5]
	s_waitcnt lgkmcnt(1)
	v_bfe_u32 v2, v6, 16, 1
	v_bfe_u32 v4, v7, 16, 1
	v_add3_u32 v2, v6, v2, s85
	v_add3_u32 v4, v7, v4, s85
	ds_read2_b32 v[6:7], v40 offset0:132 offset1:165
	v_lshrrev_b32_e32 v2, 16, v2
	v_and_or_b32 v4, v4, s86, v2
	s_waitcnt lgkmcnt(1)
	v_bfe_u32 v2, v8, 16, 1
	v_bfe_u32 v5, v9, 16, 1
	v_add3_u32 v2, v8, v2, s85
	v_add3_u32 v5, v9, v5, s85
	ds_read2_b32 v[8:9], v40 offset0:198 offset1:231
	v_lshrrev_b32_e32 v2, 16, v2
	v_and_or_b32 v5, v5, s86, v2
	s_waitcnt lgkmcnt(1)
	v_bfe_u32 v2, v6, 16, 1
	v_add3_u32 v2, v6, v2, s85
	v_bfe_u32 v6, v7, 16, 1
	v_lshrrev_b32_e32 v2, 16, v2
	v_add3_u32 v6, v7, v6, s85
	v_and_or_b32 v6, v6, s86, v2
	s_waitcnt lgkmcnt(0)
	v_bfe_u32 v2, v8, 16, 1
	v_add3_u32 v2, v8, v2, s85
	v_bfe_u32 v7, v9, 16, 1
	v_lshrrev_b32_e32 v2, 16, v2
	v_add3_u32 v7, v9, v7, s85
	v_and_or_b32 v7, v7, s86, v2
	v_lshl_add_u64 v[8:9], s[42:43], 1, v[10:11]
	v_lshlrev_b32_e32 v2, 1, v0
	v_lshl_add_u64 v[8:9], v[8:9], 0, v[2:3]
	flat_store_dwordx4 v[8:9], v[4:7] nt
.LBB0_318:
	s_or_b64 exec, exec, s[4:5]
	s_nop 0
	v_add_u32_e32 v4, s40, v65
	v_cmp_gt_i32_e32 vcc, s83, v4
	s_and_saveexec_b64 s[4:5], vcc
	s_cbranch_execz .LBB0_320
	ds_read2_b32 v[6:7], v40 offset0:8 offset1:41
	v_ashrrev_i32_e32 v5, 31, v4
	ds_read2_b32 v[8:9], v40 offset0:74 offset1:107
	v_lshlrev_b64 v[4:5], 11, v[4:5]
	v_lshl_add_u64 v[10:11], s[30:31], 0, v[4:5]
	s_waitcnt lgkmcnt(0)
	v_bfe_u32 v2, v6, 16, 1
	v_bfe_u32 v4, v7, 16, 1
	v_add3_u32 v2, v6, v2, s85
	v_add3_u32 v4, v7, v4, s85
	ds_read2_b32 v[6:7], v40 offset0:140 offset1:173
	v_lshrrev_b32_e32 v2, 16, v2
	v_and_or_b32 v4, v4, s86, v2
	v_bfe_u32 v2, v8, 16, 1
	v_bfe_u32 v5, v9, 16, 1
	v_add3_u32 v2, v8, v2, s85
	v_add3_u32 v5, v9, v5, s85
	ds_read2_b32 v[8:9], v40 offset0:206 offset1:239
	v_lshrrev_b32_e32 v2, 16, v2
	v_and_or_b32 v5, v5, s86, v2
	s_waitcnt lgkmcnt(0)
	v_bfe_u32 v2, v6, 16, 1
	v_add3_u32 v2, v6, v2, s85
	v_bfe_u32 v6, v7, 16, 1
	v_lshrrev_b32_e32 v2, 16, v2
	v_add3_u32 v6, v7, v6, s85
	v_and_or_b32 v6, v6, s86, v2
	v_bfe_u32 v2, v8, 16, 1
	v_add3_u32 v2, v8, v2, s85
	v_bfe_u32 v7, v9, 16, 1
	v_lshrrev_b32_e32 v2, 16, v2
	v_add3_u32 v7, v9, v7, s85
	v_and_or_b32 v7, v7, s86, v2
	v_lshl_add_u64 v[8:9], s[42:43], 1, v[10:11]
	v_lshlrev_b32_e32 v2, 1, v0
	v_lshl_add_u64 v[8:9], v[8:9], 0, v[2:3]
	flat_store_dwordx4 v[8:9], v[4:7] nt
.LBB0_320:
	s_or_b64 exec, exec, s[4:5]
	s_nop 0
	v_add_u32_e32 v4, s40, v66
	v_cmp_gt_i32_e32 vcc, s83, v4
	s_and_saveexec_b64 s[4:5], vcc
	s_cbranch_execz .LBB0_322
	ds_read2_b32 v[6:7], v40 offset0:16 offset1:49
	v_ashrrev_i32_e32 v5, 31, v4
	ds_read2_b32 v[8:9], v40 offset0:82 offset1:115
	v_lshlrev_b64 v[4:5], 11, v[4:5]
	v_lshl_add_u64 v[10:11], s[30:31], 0, v[4:5]
	s_waitcnt lgkmcnt(0)
	v_bfe_u32 v2, v6, 16, 1
	v_bfe_u32 v4, v7, 16, 1
	v_add3_u32 v2, v6, v2, s85
	v_add3_u32 v4, v7, v4, s85
	ds_read2_b32 v[6:7], v40 offset0:148 offset1:181
	v_lshrrev_b32_e32 v2, 16, v2
	v_and_or_b32 v4, v4, s86, v2
	v_bfe_u32 v2, v8, 16, 1
	v_bfe_u32 v5, v9, 16, 1
	v_add3_u32 v2, v8, v2, s85
	v_add3_u32 v5, v9, v5, s85
	ds_read2_b32 v[8:9], v40 offset0:214 offset1:247
	v_lshrrev_b32_e32 v2, 16, v2
	v_and_or_b32 v5, v5, s86, v2
	s_waitcnt lgkmcnt(0)
	v_bfe_u32 v2, v6, 16, 1
	v_add3_u32 v2, v6, v2, s85
	v_bfe_u32 v6, v7, 16, 1
	v_lshrrev_b32_e32 v2, 16, v2
	v_add3_u32 v6, v7, v6, s85
	v_and_or_b32 v6, v6, s86, v2
	v_bfe_u32 v2, v8, 16, 1
	v_add3_u32 v2, v8, v2, s85
	v_bfe_u32 v7, v9, 16, 1
	v_lshrrev_b32_e32 v2, 16, v2
	v_add3_u32 v7, v9, v7, s85
	v_and_or_b32 v7, v7, s86, v2
	v_lshl_add_u64 v[8:9], s[42:43], 1, v[10:11]
	v_lshlrev_b32_e32 v2, 1, v0
	v_lshl_add_u64 v[8:9], v[8:9], 0, v[2:3]
	flat_store_dwordx4 v[8:9], v[4:7] nt
.LBB0_322:
	s_or_b64 exec, exec, s[4:5]
	s_nop 0
	v_add_u32_e32 v4, s40, v67
	v_cmp_gt_i32_e32 vcc, s83, v4
	s_and_saveexec_b64 s[4:5], vcc
	s_cbranch_execz .LBB0_324
	ds_read2_b32 v[6:7], v40 offset0:24 offset1:57
	v_ashrrev_i32_e32 v5, 31, v4
	ds_read2_b32 v[8:9], v40 offset0:90 offset1:123
	v_lshlrev_b64 v[4:5], 11, v[4:5]
	v_lshl_add_u64 v[10:11], s[30:31], 0, v[4:5]
	s_waitcnt lgkmcnt(0)
	v_bfe_u32 v2, v6, 16, 1
	v_bfe_u32 v4, v7, 16, 1
	v_add3_u32 v2, v6, v2, s85
	v_add3_u32 v4, v7, v4, s85
	ds_read2_b32 v[6:7], v40 offset0:156 offset1:189
	v_lshrrev_b32_e32 v2, 16, v2
	v_and_or_b32 v4, v4, s86, v2
	v_bfe_u32 v2, v8, 16, 1
	v_bfe_u32 v5, v9, 16, 1
	v_add3_u32 v2, v8, v2, s85
	v_add3_u32 v5, v9, v5, s85
	ds_read2_b32 v[8:9], v40 offset0:222 offset1:255
	v_lshrrev_b32_e32 v2, 16, v2
	v_and_or_b32 v5, v5, s86, v2
	s_waitcnt lgkmcnt(0)
	v_bfe_u32 v2, v6, 16, 1
	v_add3_u32 v2, v6, v2, s85
	v_bfe_u32 v6, v7, 16, 1
	v_lshrrev_b32_e32 v2, 16, v2
	v_add3_u32 v6, v7, v6, s85
	v_and_or_b32 v6, v6, s86, v2
	v_bfe_u32 v2, v8, 16, 1
	v_add3_u32 v2, v8, v2, s85
	v_bfe_u32 v7, v9, 16, 1
	v_lshrrev_b32_e32 v2, 16, v2
	v_add3_u32 v7, v9, v7, s85
	v_and_or_b32 v7, v7, s86, v2
	v_lshl_add_u64 v[8:9], s[42:43], 1, v[10:11]
	v_lshlrev_b32_e32 v2, 1, v0
	v_lshl_add_u64 v[8:9], v[8:9], 0, v[2:3]
	flat_store_dwordx4 v[8:9], v[4:7] nt

; #define LAS __attribute__((address_space(3)))
; __device__ __forceinline__ unsigned pk2(float lo, float hi) { return f2bf(lo) | (f2bf(hi) << 16); }
; __device__ __forceinline__ bf16_t* tmap(int mode, int n, bf16_t* d0, bf16_t* d1, int K, float& cs) {
;     ...
;     if (mode == 0) return d0 + (size_t)n * K;
; __device__ __forceinline__ void transpose_item(const float* W, int K, int N, int mode, const float* kscale, bf16_t* d0, bf16_t* d1, LAS float* scr, int item, int lane) {
;     ...
; #pragma unroll
;     for (int i = 0; i < 32; ++i) { const int kk = 2 * i + (lane >> 5); scr[kk * 33 + (lane & 31)] = tv[i]; }
;     asm volatile("s_waitcnt lgkmcnt(0)" ::: "memory");
;     const int c = lane & 7;
; #pragma unroll
;     for (int j = 0; j < 4; ++j) { const int n = (lane >> 3) + 8 * j; const LAS float* s = scr + (8 * c) * 33 + n;
;         if (n0 + n < N) { float cs; bf16_t* dst = tmap(mode, n0 + n, d0, d1, K, cs);
;             u32x4 o; o.x = pk2(s[0 * 33] * cs, s[1 * 33] * cs); o.y = pk2(s[2 * 33] * cs, s[3 * 33] * cs); o.z = pk2(s[4 * 33] * cs, s[5 * 33] * cs); o.w = pk2(s[6 * 33] * cs, s[7 * 33] * cs);
;             *(u32x4*)(dst + k0 + 8 * c) = o; } }
.LBB0_391:
	s_or_b64 exec, exec, s[62:63]
	v_add_u32_e32 v2, 0x400, v38
	s_waitcnt vmcnt(0)
	ds_write2_b32 v38, v6, v7 offset1:66
	ds_write2_b32 v38, v9, v8 offset0:132 offset1:198
	ds_write2_b32 v2, v11, v10 offset0:8 offset1:74
	ds_write2_b32 v2, v13, v12 offset0:140 offset1:206
	v_add_u32_e32 v2, 0x800, v38
	ds_write2_b32 v2, v15, v14 offset0:16 offset1:82
	ds_write2_b32 v2, v17, v16 offset0:148 offset1:214
	v_add_u32_e32 v2, 0xc00, v38
	ds_write2_b32 v2, v19, v18 offset0:24 offset1:90
	ds_write2_b32 v2, v21, v20 offset0:156 offset1:222
	v_add_u32_e32 v2, 0x1000, v38
	ds_write2_b32 v2, v23, v22 offset0:32 offset1:98
	ds_write2_b32 v2, v25, v24 offset0:164 offset1:230
	v_add_u32_e32 v2, 0x1400, v38
	ds_write2_b32 v2, v27, v26 offset0:40 offset1:106
	ds_write2_b32 v2, v29, v28 offset0:172 offset1:238
	v_add_u32_e32 v2, 0x1800, v38
	ds_write2_b32 v2, v31, v30 offset0:48 offset1:114
	ds_write2_b32 v2, v33, v32 offset0:180 offset1:246
	v_add_u32_e32 v2, 0x1c00, v38
	s_sub_i32 s40, 0, s40
	ds_write2_b32 v2, v35, v34 offset0:56 offset1:122
	ds_write2_b32 v2, v37, v36 offset0:188 offset1:254
	s_waitcnt lgkmcnt(0)
	s_add_i32 s40, s40, s74
	v_add_u32_e32 v4, s40, v69
	v_cmp_gt_i32_e32 vcc, s83, v4
	s_and_saveexec_b64 s[4:5], vcc
	s_cbranch_execz .LBB0_393
	ds_read2_b32 v[6:7], v40 offset1:33
	v_ashrrev_i32_e32 v5, 31, v4
	ds_read2_b32 v[8:9], v40 offset0:66 offset1:99
	v_lshlrev_b64 v[4:5], 11, v[4:5]
	v_lshl_add_u64 v[10:11], s[28:29], 0, v[4:5]
	s_waitcnt lgkmcnt(1)
	v_bfe_u32 v2, v6, 16, 1
	v_bfe_u32 v4, v7, 16, 1
	v_add3_u32 v2, v6, v2, s85
	v_add3_u32 v4, v7, v4, s85
	ds_read2_b32 v[6:7], v40 offset0:132 offset1:165
	v_lshrrev_b32_e32 v2, 16, v2
	v_and_or_b32 v4, v4, s86, v2
	s_waitcnt lgkmcnt(1)
	v_bfe_u32 v2, v8, 16, 1
	v_bfe_u32 v5, v9, 16, 1
	v_add3_u32 v2, v8, v2, s85
	v_add3_u32 v5, v9, v5, s85
	ds_read2_b32 v[8:9], v40 offset0:198 offset1:231
	v_lshrrev_b32_e32 v2, 16, v2
	v_and_or_b32 v5, v5, s86, v2
	s_waitcnt lgkmcnt(1)
	v_bfe_u32 v2, v6, 16, 1
	v_add3_u32 v2, v6, v2, s85
	v_bfe_u32 v6, v7, 16, 1
	v_lshrrev_b32_e32 v2, 16, v2
	v_add3_u32 v6, v7, v6, s85
	v_and_or_b32 v6, v6, s86, v2
	s_waitcnt lgkmcnt(0)
	v_bfe_u32 v2, v8, 16, 1
	v_add3_u32 v2, v8, v2, s85
	v_bfe_u32 v7, v9, 16, 1
	v_lshrrev_b32_e32 v2, 16, v2
	v_add3_u32 v7, v9, v7, s85
	v_and_or_b32 v7, v7, s86, v2
	v_lshl_add_u64 v[8:9], s[42:43], 1, v[10:11]
	v_lshlrev_b32_e32 v2, 1, v0
	v_lshl_add_u64 v[8:9], v[8:9], 0, v[2:3]
	flat_store_dwordx4 v[8:9], v[4:7] nt
.LBB0_393:
	s_or_b64 exec, exec, s[4:5]
	s_nop 0
	v_add_u32_e32 v4, s40, v70
	v_cmp_gt_i32_e32 vcc, s83, v4
	s_and_saveexec_b64 s[4:5], vcc
	s_cbranch_execz .LBB0_395
	ds_read2_b32 v[6:7], v40 offset0:8 offset1:41
	v_ashrrev_i32_e32 v5, 31, v4
	ds_read2_b32 v[8:9], v40 offset0:74 offset1:107
	v_lshlrev_b64 v[4:5], 11, v[4:5]
	v_lshl_add_u64 v[10:11], s[28:29], 0, v[4:5]
	s_waitcnt lgkmcnt(0)
	v_bfe_u32 v2, v6, 16, 1
	v_bfe_u32 v4, v7, 16, 1
	v_add3_u32 v2, v6, v2, s85
	v_add3_u32 v4, v7, v4, s85
	ds_read2_b32 v[6:7], v40 offset0:140 offset1:173
	v_lshrrev_b32_e32 v2, 16, v2
	v_and_or_b32 v4, v4, s86, v2
	v_bfe_u32 v2, v8, 16, 1
	v_bfe_u32 v5, v9, 16, 1
	v_add3_u32 v2, v8, v2, s85
	v_add3_u32 v5, v9, v5, s85
	ds_read2_b32 v[8:9], v40 offset0:206 offset1:239
	v_lshrrev_b32_e32 v2, 16, v2
	v_and_or_b32 v5, v5, s86, v2
	s_waitcnt lgkmcnt(0)
	v_bfe_u32 v2, v6, 16, 1
	v_add3_u32 v2, v6, v2, s85
	v_bfe_u32 v6, v7, 16, 1
	v_lshrrev_b32_e32 v2, 16, v2
	v_add3_u32 v6, v7, v6, s85
	v_and_or_b32 v6, v6, s86, v2
	v_bfe_u32 v2, v8, 16, 1
	v_add3_u32 v2, v8, v2, s85
	v_bfe_u32 v7, v9, 16, 1
	v_lshrrev_b32_e32 v2, 16, v2
	v_add3_u32 v7, v9, v7, s85
	v_and_or_b32 v7, v7, s86, v2
	v_lshl_add_u64 v[8:9], s[42:43], 1, v[10:11]
	v_lshlrev_b32_e32 v2, 1, v0
	v_lshl_add_u64 v[8:9], v[8:9], 0, v[2:3]
	flat_store_dwordx4 v[8:9], v[4:7] nt
.LBB0_395:
	s_or_b64 exec, exec, s[4:5]
	s_nop 0
	v_add_u32_e32 v4, s40, v71
	v_cmp_gt_i32_e32 vcc, s83, v4
	s_and_saveexec_b64 s[4:5], vcc
	s_cbranch_execz .LBB0_397
	ds_read2_b32 v[6:7], v40 offset0:16 offset1:49
	v_ashrrev_i32_e32 v5, 31, v4
	ds_read2_b32 v[8:9], v40 offset0:82 offset1:115
	v_lshlrev_b64 v[4:5], 11, v[4:5]
	v_lshl_add_u64 v[10:11], s[28:29], 0, v[4:5]
	s_waitcnt lgkmcnt(0)
	v_bfe_u32 v2, v6, 16, 1
	v_bfe_u32 v4, v7, 16, 1
	v_add3_u32 v2, v6, v2, s85
	v_add3_u32 v4, v7, v4, s85
	ds_read2_b32 v[6:7], v40 offset0:148 offset1:181
	v_lshrrev_b32_e32 v2, 16, v2
	v_and_or_b32 v4, v4, s86, v2
	v_bfe_u32 v2, v8, 16, 1
	v_bfe_u32 v5, v9, 16, 1
	v_add3_u32 v2, v8, v2, s85
	v_add3_u32 v5, v9, v5, s85
	ds_read2_b32 v[8:9], v40 offset0:214 offset1:247
	v_lshrrev_b32_e32 v2, 16, v2
	v_and_or_b32 v5, v5, s86, v2
	s_waitcnt lgkmcnt(0)
	v_bfe_u32 v2, v6, 16, 1
	v_add3_u32 v2, v6, v2, s85
	v_bfe_u32 v6, v7, 16, 1
	v_lshrrev_b32_e32 v2, 16, v2
	v_add3_u32 v6, v7, v6, s85
	v_and_or_b32 v6, v6, s86, v2
	v_bfe_u32 v2, v8, 16, 1
	v_add3_u32 v2, v8, v2, s85
	v_bfe_u32 v7, v9, 16, 1
	v_lshrrev_b32_e32 v2, 16, v2
	v_add3_u32 v7, v9, v7, s85
	v_and_or_b32 v7, v7, s86, v2
	v_lshl_add_u64 v[8:9], s[42:43], 1, v[10:11]
	v_lshlrev_b32_e32 v2, 1, v0
	v_lshl_add_u64 v[8:9], v[8:9], 0, v[2:3]
	flat_store_dwordx4 v[8:9], v[4:7] nt
.LBB0_397:
	s_or_b64 exec, exec, s[4:5]
	s_nop 0
	v_add_u32_e32 v4, s40, v72
	v_cmp_gt_i32_e32 vcc, s83, v4
	s_and_saveexec_b64 s[4:5], vcc
	s_cbranch_execz .LBB0_399
	ds_read2_b32 v[6:7], v40 offset0:24 offset1:57
	v_ashrrev_i32_e32 v5, 31, v4
	ds_read2_b32 v[8:9], v40 offset0:90 offset1:123
	v_lshlrev_b64 v[4:5], 11, v[4:5]
	v_lshl_add_u64 v[10:11], s[28:29], 0, v[4:5]
	s_waitcnt lgkmcnt(0)
	v_bfe_u32 v2, v6, 16, 1
	v_bfe_u32 v4, v7, 16, 1
	v_add3_u32 v2, v6, v2, s85
	v_add3_u32 v4, v7, v4, s85
	ds_read2_b32 v[6:7], v40 offset0:156 offset1:189
	v_lshrrev_b32_e32 v2, 16, v2
	v_and_or_b32 v4, v4, s86, v2
	v_bfe_u32 v2, v8, 16, 1
	v_bfe_u32 v5, v9, 16, 1
	v_add3_u32 v2, v8, v2, s85
	v_add3_u32 v5, v9, v5, s85
	ds_read2_b32 v[8:9], v40 offset0:222 offset1:255
	v_lshrrev_b32_e32 v2, 16, v2
	v_and_or_b32 v5, v5, s86, v2
	s_waitcnt lgkmcnt(0)
	v_bfe_u32 v2, v6, 16, 1
	v_add3_u32 v2, v6, v2, s85
	v_bfe_u32 v6, v7, 16, 1
	v_lshrrev_b32_e32 v2, 16, v2
	v_add3_u32 v6, v7, v6, s85
	v_and_or_b32 v6, v6, s86, v2
	v_bfe_u32 v2, v8, 16, 1
	v_add3_u32 v2, v8, v2, s85
	v_bfe_u32 v7, v9, 16, 1
	v_lshrrev_b32_e32 v2, 16, v2
	v_add3_u32 v7, v9, v7, s85
	v_and_or_b32 v7, v7, s86, v2
	v_lshl_add_u64 v[8:9], s[42:43], 1, v[10:11]
	v_lshlrev_b32_e32 v2, 1, v0
	v_lshl_add_u64 v[8:9], v[8:9], 0, v[2:3]
	flat_store_dwordx4 v[8:9], v[4:7] nt

; #define LAS __attribute__((address_space(3)))
; __device__ __forceinline__ unsigned pk2(float lo, float hi) { return f2bf(lo) | (f2bf(hi) << 16); }
; __device__ __forceinline__ bf16_t* tmap(int mode, int n, bf16_t* d0, bf16_t* d1, int K, float& cs) {
;     ...
;     { const int hh = n >> 8, d = n & 255;
;       if (d < 128) return d0 + (size_t)(hh * 128 + d) * K;
;       return d1 + (size_t)(hh * 128 + d - 128) * K; }
; __device__ __forceinline__ void transpose_item(const float* W, int K, int N, int mode, const float* kscale, bf16_t* d0, bf16_t* d1, LAS float* scr, int item, int lane) {
;     ...
; #pragma unroll
;     for (int i = 0; i < 32; ++i) { const int kk = 2 * i + (lane >> 5); scr[kk * 33 + (lane & 31)] = tv[i]; }
;     asm volatile("s_waitcnt lgkmcnt(0)" ::: "memory");
;     const int c = lane & 7;
; #pragma unroll
;     for (int j = 0; j < 4; ++j) { const int n = (lane >> 3) + 8 * j; const LAS float* s = scr + (8 * c) * 33 + n;
;         if (n0 + n < N) { float cs; bf16_t* dst = tmap(mode, n0 + n, d0, d1, K, cs);
;             u32x4 o; o.x = pk2(s[0 * 33] * cs, s[1 * 33] * cs); o.y = pk2(s[2 * 33] * cs, s[3 * 33] * cs); o.z = pk2(s[4 * 33] * cs, s[5 * 33] * cs); o.w = pk2(s[6 * 33] * cs, s[7 * 33] * cs);
;             *(u32x4*)(dst + k0 + 8 * c) = o; } }
.LBB0_404:
	v_add_u32_e32 v2, 0x400, v38
	s_waitcnt vmcnt(0)
	ds_write2_b32 v38, v4, v5 offset1:66
	ds_write2_b32 v38, v8, v9 offset0:132 offset1:198
	ds_write2_b32 v2, v6, v7 offset0:8 offset1:74
	ds_write2_b32 v2, v10, v11 offset0:140 offset1:206
	v_add_u32_e32 v2, 0x800, v38
	ds_write2_b32 v2, v12, v13 offset0:16 offset1:82
	ds_write2_b32 v2, v16, v17 offset0:148 offset1:214
	v_add_u32_e32 v2, 0xc00, v38
	ds_write2_b32 v2, v14, v15 offset0:24 offset1:90
	ds_write2_b32 v2, v18, v19 offset0:156 offset1:222
	v_add_u32_e32 v2, 0x1000, v38
	ds_write2_b32 v2, v20, v21 offset0:32 offset1:98
	ds_write2_b32 v2, v24, v25 offset0:164 offset1:230
	v_add_u32_e32 v2, 0x1400, v38
	s_lshl_b32 s5, s5, 4
	ds_write2_b32 v2, v22, v23 offset0:40 offset1:106
	ds_write2_b32 v2, v26, v27 offset0:172 offset1:238
	v_add_u32_e32 v2, 0x1800, v38
	s_and_b32 s40, s5, 0x380
	ds_write2_b32 v2, v28, v29 offset0:48 offset1:114
	ds_write2_b32 v2, v34, v35 offset0:180 offset1:246
	v_add_u32_e32 v2, 0x1c00, v38
	s_add_i32 s41, s40, 0xffffff80
	s_and_b32 s48, s4, 0xe0
	ds_write2_b32 v2, v32, v33 offset0:56 offset1:122
	ds_write2_b32 v2, v30, v31 offset0:188 offset1:254
	v_or_b32_e32 v2, s48, v39
	s_cmpk_lt_u32 s48, 0x80
	v_or_b32_e32 v4, s40, v2
	v_add_u32_e32 v2, s41, v2
	s_cselect_b64 vcc, -1, 0
	v_cndmask_b32_e32 v4, v2, v4, vcc
	v_ashrrev_i32_e32 v5, 31, v4
	s_and_b64 s[4:5], vcc, exec
	s_waitcnt lgkmcnt(0)
	s_cselect_b32 s5, s23, s70
	s_cselect_b32 s4, s21, s59
	v_lshlrev_b64 v[4:5], 9, v[4:5]
	v_lshl_add_u64 v[8:9], s[4:5], 0, v[4:5]
	ds_read_b32 v2, v40
	ds_read_b32 v4, v40 offset:132
	ds_read_b32 v5, v40 offset:264
	ds_read_b32 v6, v40 offset:396
	ds_read_b32 v7, v40 offset:528
	ds_read_b32 v10, v40 offset:660
	ds_read_b32 v11, v40 offset:792
	ds_read_b32 v12, v40 offset:924
	s_waitcnt lgkmcnt(7)
	v_bfe_u32 v13, v2, 16, 1
	v_add3_u32 v2, v2, v13, s85
	s_waitcnt lgkmcnt(6)
	v_bfe_u32 v13, v4, 16, 1
	v_lshrrev_b32_e32 v2, 16, v2
	v_add3_u32 v4, v4, v13, s85
	v_and_or_b32 v4, v4, s86, v2
	s_waitcnt lgkmcnt(5)
	v_bfe_u32 v2, v5, 16, 1
	v_add3_u32 v2, v5, v2, s85
	s_waitcnt lgkmcnt(4)
	v_bfe_u32 v5, v6, 16, 1
	v_lshrrev_b32_e32 v2, 16, v2
	v_add3_u32 v5, v6, v5, s85
	v_and_or_b32 v5, v5, s86, v2
	s_waitcnt lgkmcnt(3)
	v_bfe_u32 v2, v7, 16, 1
	v_add3_u32 v2, v7, v2, s85
	s_waitcnt lgkmcnt(2)
	v_bfe_u32 v6, v10, 16, 1
	v_lshrrev_b32_e32 v2, 16, v2
	v_add3_u32 v6, v10, v6, s85
	v_and_or_b32 v6, v6, s86, v2
	s_waitcnt lgkmcnt(1)
	v_bfe_u32 v2, v11, 16, 1
	v_add3_u32 v2, v11, v2, s85
	s_waitcnt lgkmcnt(0)
	v_bfe_u32 v7, v12, 16, 1
	v_lshrrev_b32_e32 v2, 16, v2
	v_add3_u32 v7, v12, v7, s85
	s_lshl_b64 s[62:63], s[42:43], 1
	v_and_or_b32 v7, v7, s86, v2
	v_lshl_add_u64 v[8:9], v[8:9], 0, s[62:63]
	v_lshlrev_b32_e32 v2, 1, v0
	v_lshl_add_u64 v[8:9], v[8:9], 0, v[2:3]
	flat_store_dwordx4 v[8:9], v[4:7] nt
	s_nop 1
	v_or_b32_e32 v4, s48, v41
	v_or_b32_e32 v5, s40, v4
	v_add_u32_e32 v4, s41, v4
	v_cndmask_b32_e32 v4, v4, v5, vcc
	v_ashrrev_i32_e32 v5, 31, v4
	v_lshlrev_b64 v[4:5], 9, v[4:5]
	v_lshl_add_u64 v[8:9], s[4:5], 0, v[4:5]
	ds_read_b32 v4, v40 offset:32
	ds_read_b32 v5, v40 offset:164
	ds_read_b32 v6, v40 offset:296
	ds_read_b32 v7, v40 offset:428
	ds_read_b32 v10, v40 offset:560
	ds_read_b32 v11, v40 offset:692
	ds_read_b32 v12, v40 offset:824
	ds_read_b32 v13, v40 offset:956
	s_waitcnt lgkmcnt(0)
	v_bfe_u32 v14, v4, 16, 1
	v_add3_u32 v4, v4, v14, s85
	v_bfe_u32 v14, v5, 16, 1
	v_lshrrev_b32_e32 v4, 16, v4
	v_add3_u32 v5, v5, v14, s85
	v_and_or_b32 v4, v5, s86, v4
	v_bfe_u32 v5, v6, 16, 1
	v_add3_u32 v5, v6, v5, s85
	v_bfe_u32 v6, v7, 16, 1
	v_lshrrev_b32_e32 v5, 16, v5
	v_add3_u32 v6, v7, v6, s85
	v_and_or_b32 v5, v6, s86, v5
	v_bfe_u32 v6, v10, 16, 1
	v_add3_u32 v6, v10, v6, s85
	v_bfe_u32 v7, v11, 16, 1
	v_lshrrev_b32_e32 v6, 16, v6
	v_add3_u32 v7, v11, v7, s85
	v_and_or_b32 v6, v7, s86, v6
	v_bfe_u32 v7, v12, 16, 1
	v_add3_u32 v7, v12, v7, s85
	v_bfe_u32 v10, v13, 16, 1
	v_lshrrev_b32_e32 v7, 16, v7
	v_add3_u32 v10, v13, v10, s85
	v_lshl_add_u64 v[8:9], v[8:9], 0, s[62:63]
	v_and_or_b32 v7, v10, s86, v7
	v_lshl_add_u64 v[8:9], v[8:9], 0, v[2:3]
	flat_store_dwordx4 v[8:9], v[4:7] nt
	s_nop 1
	v_or_b32_e32 v4, s48, v42
	v_or_b32_e32 v5, s40, v4
	v_add_u32_e32 v4, s41, v4
	v_cndmask_b32_e32 v4, v4, v5, vcc
	v_ashrrev_i32_e32 v5, 31, v4
	v_lshlrev_b64 v[4:5], 9, v[4:5]
	v_lshl_add_u64 v[8:9], s[4:5], 0, v[4:5]
	ds_read_b32 v4, v40 offset:64
	ds_read_b32 v5, v40 offset:196
	ds_read_b32 v6, v40 offset:328
	ds_read_b32 v7, v40 offset:460
	ds_read_b32 v10, v40 offset:592
	ds_read_b32 v11, v40 offset:724
	ds_read_b32 v12, v40 offset:856
	ds_read_b32 v13, v40 offset:988
	s_waitcnt lgkmcnt(0)
	v_bfe_u32 v14, v4, 16, 1
	v_add3_u32 v4, v4, v14, s85
	v_bfe_u32 v14, v5, 16, 1
	v_lshrrev_b32_e32 v4, 16, v4
	v_add3_u32 v5, v5, v14, s85
	v_and_or_b32 v4, v5, s86, v4
	v_bfe_u32 v5, v6, 16, 1
	v_add3_u32 v5, v6, v5, s85
	v_bfe_u32 v6, v7, 16, 1
	v_lshrrev_b32_e32 v5, 16, v5
	v_add3_u32 v6, v7, v6, s85
	v_and_or_b32 v5, v6, s86, v5
	v_bfe_u32 v6, v10, 16, 1
	v_add3_u32 v6, v10, v6, s85
	v_bfe_u32 v7, v11, 16, 1
	v_lshrrev_b32_e32 v6, 16, v6
	v_add3_u32 v7, v11, v7, s85
	v_and_or_b32 v6, v7, s86, v6
	v_bfe_u32 v7, v12, 16, 1
	v_add3_u32 v7, v12, v7, s85
	v_bfe_u32 v10, v13, 16, 1
	v_lshrrev_b32_e32 v7, 16, v7
	v_add3_u32 v10, v13, v10, s85
	v_lshl_add_u64 v[8:9], v[8:9], 0, s[62:63]
	v_and_or_b32 v7, v10, s86, v7
	v_lshl_add_u64 v[8:9], v[8:9], 0, v[2:3]
	flat_store_dwordx4 v[8:9], v[4:7] nt
	s_nop 1
	v_or_b32_e32 v4, s48, v43
	v_or_b32_e32 v5, s40, v4
	v_add_u32_e32 v4, s41, v4
	v_cndmask_b32_e32 v4, v4, v5, vcc
	v_ashrrev_i32_e32 v5, 31, v4
	v_lshlrev_b64 v[4:5], 9, v[4:5]
	v_lshl_add_u64 v[8:9], s[4:5], 0, v[4:5]
	ds_read_b32 v4, v40 offset:96
	ds_read_b32 v5, v40 offset:228
	ds_read_b32 v6, v40 offset:360
	ds_read_b32 v7, v40 offset:492
	ds_read_b32 v10, v40 offset:624
	ds_read_b32 v11, v40 offset:756
	ds_read_b32 v12, v40 offset:888
	ds_read_b32 v13, v40 offset:1020
	s_waitcnt lgkmcnt(0)
	v_bfe_u32 v14, v4, 16, 1
	v_add3_u32 v4, v4, v14, s85
	v_bfe_u32 v14, v5, 16, 1
	v_lshrrev_b32_e32 v4, 16, v4
	v_add3_u32 v5, v5, v14, s85
	v_and_or_b32 v4, v5, s86, v4
	v_bfe_u32 v5, v6, 16, 1
	v_add3_u32 v5, v6, v5, s85
	v_bfe_u32 v6, v7, 16, 1
	v_lshrrev_b32_e32 v5, 16, v5
	v_add3_u32 v6, v7, v6, s85
	v_and_or_b32 v5, v6, s86, v5
	v_bfe_u32 v6, v10, 16, 1
	v_add3_u32 v6, v10, v6, s85
	v_bfe_u32 v7, v11, 16, 1
	v_lshrrev_b32_e32 v6, 16, v6
	v_add3_u32 v7, v11, v7, s85
	v_and_or_b32 v6, v7, s86, v6
	v_bfe_u32 v7, v12, 16, 1
	v_add3_u32 v7, v12, v7, s85
	v_bfe_u32 v10, v13, 16, 1
	v_lshrrev_b32_e32 v7, 16, v7
	v_add3_u32 v10, v13, v10, s85
	v_lshl_add_u64 v[8:9], v[8:9], 0, s[62:63]
	v_and_or_b32 v7, v10, s86, v7
	v_lshl_add_u64 v[8:9], v[8:9], 0, v[2:3]
	flat_store_dwordx4 v[8:9], v[4:7] nt
	s_waitcnt lgkmcnt(0)

; #define LAS __attribute__((address_space(3)))
; __device__ __forceinline__ unsigned pk2(float lo, float hi) { return f2bf(lo) | (f2bf(hi) << 16); }
; __device__ __forceinline__ bf16_t* tmap(int mode, int n, bf16_t* d0, bf16_t* d1, int K, float& cs) {
;     ...
;     if (mode == 2) {
;         cs = 0.07216878364870322f * LOG2E;
;         const int hh = n / 192, d = n - hh * 192; int r;
;         if (d < 128) r = hh * 128 + d;
;         else { const int e = d - 128, i = e & 31, hf = e >> 5; r = 1024 + hh * 64 + 8 * (i >> 2) + 4 * hf + (i & 3); }
;         return d0 + (size_t)r * K;
;     }
; __device__ __forceinline__ void transpose_item(const float* W, int K, int N, int mode, const float* kscale, bf16_t* d0, bf16_t* d1, LAS float* scr, int item, int lane) {
;     ...
;     for (int i = 0; i < 32; ++i) { const int kk = 2 * i + (lane >> 5); scr[kk * 33 + (lane & 31)] = tv[i]; }
;     asm volatile("s_waitcnt lgkmcnt(0)" ::: "memory");
;     const int c = lane & 7;
; #pragma unroll
;     for (int j = 0; j < 4; ++j) { const int n = (lane >> 3) + 8 * j; const LAS float* s = scr + (8 * c) * 33 + n;
;         if (n0 + n < N) { float cs; bf16_t* dst = tmap(mode, n0 + n, d0, d1, K, cs);
;             u32x4 o; o.x = pk2(s[0 * 33] * cs, s[1 * 33] * cs); o.y = pk2(s[2 * 33] * cs, s[3 * 33] * cs); o.z = pk2(s[4 * 33] * cs, s[5 * 33] * cs); o.w = pk2(s[6 * 33] * cs, s[7 * 33] * cs);
;             *(u32x4*)(dst + k0 + 8 * c) = o; } }
.LBB0_471:
	v_add_u32_e32 v2, 0x400, v38
	s_waitcnt vmcnt(0)
	ds_write2_b32 v38, v4, v5 offset1:66
	ds_write2_b32 v38, v6, v7 offset0:132 offset1:198
	ds_write2_b32 v2, v8, v9 offset0:8 offset1:74
	ds_write2_b32 v2, v10, v11 offset0:140 offset1:206
	v_add_u32_e32 v2, 0x800, v38
	ds_write2_b32 v2, v12, v13 offset0:16 offset1:82
	ds_write2_b32 v2, v14, v15 offset0:148 offset1:214
	v_add_u32_e32 v2, 0xc00, v38
	ds_write2_b32 v2, v16, v17 offset0:24 offset1:90
	ds_write2_b32 v2, v20, v21 offset0:156 offset1:222
	v_add_u32_e32 v2, 0x1000, v38
	ds_write2_b32 v2, v22, v23 offset0:32 offset1:98
	ds_write2_b32 v2, v24, v25 offset0:164 offset1:230
	v_add_u32_e32 v2, 0x1400, v38
	ds_write2_b32 v2, v26, v27 offset0:40 offset1:106
	ds_write2_b32 v2, v28, v29 offset0:172 offset1:238
	v_add_u32_e32 v2, 0x1800, v38
	ds_write2_b32 v2, v30, v31 offset0:48 offset1:114
	ds_write2_b32 v2, v32, v33 offset0:180 offset1:246
	v_add_u32_e32 v2, 0x1c00, v38
	ds_write2_b32 v2, v34, v35 offset0:56 offset1:122
	ds_write2_b32 v2, v36, v37 offset0:188 offset1:254
	s_waitcnt lgkmcnt(0)
	v_add_u32_e32 v2, s67, v76
	v_cmp_gt_i32_e32 vcc, s89, v2
	v_add_u32_e32 v6, s74, v39
	s_and_saveexec_b64 s[4:5], vcc
	s_cbranch_execz .LBB0_477
	v_mul_hi_i32 v2, v2, s90
	v_lshrrev_b32_e32 v4, 31, v2
	v_ashrrev_i32_e32 v2, 5, v2
	v_add_u32_e32 v2, v2, v4
	v_mul_lo_u32 v4, v2, s91
	v_add3_u32 v5, v6, v4, s66
	v_add_u32_e32 v4, 0xfffc1400, v5
	v_cmp_lt_i32_e32 vcc, s92, v4
	v_lshlrev_b32_e32 v2, 6, v2
	s_and_saveexec_b64 s[40:41], vcc
	s_xor_b64 s[62:63], exec, s[40:41]
	v_add_u32_e32 v4, 0xfffc1380, v5
	v_lshrrev_b32_e32 v4, 3, v4
	v_add3_u32 v4, v44, v2, v4
	s_andn2_saveexec_b64 s[62:63], s[62:63]
	v_sub_u32_e32 v2, v6, v2
	v_add_u32_e32 v2, s66, v2
	v_add_u32_e32 v4, 0xfffc1400, v2
	s_or_b64 exec, exec, s[62:63]
	ds_read2_b32 v[8:9], v40 offset1:33
	ds_read2_b32 v[10:11], v40 offset0:66 offset1:99
	ds_read2_b32 v[14:15], v40 offset0:132 offset1:165
	ds_read2_b32 v[16:17], v40 offset0:198 offset1:231
	v_ashrrev_i32_e32 v5, 31, v4
	v_lshlrev_b64 v[4:5], 10, v[4:5]
	s_waitcnt lgkmcnt(0)
	v_mov_b32_e32 v12, v8
	v_mov_b32_e32 v13, v10
	v_mov_b32_e32 v10, v9
	v_pk_mul_f32 v[8:9], v[10:11], s[58:59] op_sel_hi:[1,0]
	v_mov_b32_e32 v10, v14
	v_mov_b32_e32 v11, v16
	v_mov_b32_e32 v16, v15
	v_pk_mul_f32 v[10:11], v[10:11], s[58:59] op_sel_hi:[1,0]
	v_pk_mul_f32 v[14:15], v[16:17], s[58:59] op_sel_hi:[1,0]
	v_bfe_u32 v17, v8, 16, 1
	v_pk_mul_f32 v[12:13], v[12:13], s[58:59] op_sel_hi:[1,0]
	v_bfe_u32 v2, v15, 16, 1
	v_bfe_u32 v7, v14, 16, 1
	v_bfe_u32 v16, v9, 16, 1
	v_add3_u32 v8, v8, v17, s85
	v_bfe_u32 v17, v11, 16, 1
	v_add3_u32 v9, v9, v16, s85
	v_add3_u32 v7, v14, v7, s85
	v_add3_u32 v2, v15, v2, s85
	v_bfe_u32 v14, v12, 16, 1
	v_bfe_u32 v15, v13, 16, 1
	v_bfe_u32 v16, v10, 16, 1
	v_add3_u32 v11, v11, v17, s85
	v_lshl_add_u64 v[4:5], s[26:27], 0, v[4:5]
	v_add3_u32 v10, v10, v16, s85
	v_add3_u32 v13, v13, v15, s85
	v_add3_u32 v12, v12, v14, s85
	v_lshrrev_b32_e32 v11, 16, v11
	s_lshl_b32 s42, s65, 1
	v_lshrrev_b32_e32 v12, 16, v12
	v_lshrrev_b32_e32 v13, 16, v13
	v_lshrrev_b32_e32 v10, 16, v10
	v_and_or_b32 v11, v2, s86, v11
	v_lshl_add_u64 v[4:5], v[4:5], 0, s[42:43]
	v_lshlrev_b32_e32 v2, 1, v0
	v_and_or_b32 v10, v7, s86, v10
	v_and_or_b32 v9, v9, s86, v13
	v_and_or_b32 v8, v8, s86, v12
	v_lshl_add_u64 v[4:5], v[4:5], 0, v[2:3]
	flat_store_dwordx4 v[4:5], v[8:11] nt
.LBB0_477:
	s_or_b64 exec, exec, s[4:5]
	v_add_u32_e32 v2, s67, v75
	v_cmp_gt_i32_e32 vcc, s89, v2
	s_and_saveexec_b64 s[4:5], vcc
	s_cbranch_execz .LBB0_483
	v_mul_hi_i32 v2, v2, s90
	v_lshrrev_b32_e32 v4, 31, v2
	v_ashrrev_i32_e32 v2, 5, v2
	v_add_u32_e32 v2, v2, v4
	v_mul_lo_u32 v4, v2, s91
	v_add3_u32 v5, v6, v4, s66
	v_add_u32_e32 v4, 0xfffc1408, v5
	v_cmp_lt_i32_e32 vcc, s92, v4
	v_lshlrev_b32_e32 v2, 6, v2
	s_and_saveexec_b64 s[40:41], vcc
	s_xor_b64 s[62:63], exec, s[40:41]
	v_add_u32_e32 v4, 0xfffc1388, v5
	v_lshrrev_b32_e32 v4, 3, v4
	v_and_b32_e32 v4, 0x1ffffffc, v4
	v_add3_u32 v4, v45, v2, v4
	s_andn2_saveexec_b64 s[62:63], s[62:63]
	v_sub_u32_e32 v2, v6, v2
	v_add_u32_e32 v2, s66, v2
	v_add_u32_e32 v4, 0xfffc1408, v2
	s_or_b64 exec, exec, s[62:63]
	ds_read2_b32 v[8:9], v40 offset0:8 offset1:41
	ds_read2_b32 v[10:11], v40 offset0:74 offset1:107
	ds_read2_b32 v[14:15], v40 offset0:140 offset1:173
	ds_read2_b32 v[16:17], v40 offset0:206 offset1:239
	v_ashrrev_i32_e32 v5, 31, v4
	v_lshlrev_b64 v[4:5], 10, v[4:5]
	s_waitcnt lgkmcnt(0)
	v_mov_b32_e32 v12, v8
	v_mov_b32_e32 v13, v10
	v_mov_b32_e32 v10, v9
	v_pk_mul_f32 v[8:9], v[10:11], s[58:59] op_sel_hi:[1,0]
	v_mov_b32_e32 v10, v14
	v_mov_b32_e32 v11, v16
	v_mov_b32_e32 v16, v15
	v_pk_mul_f32 v[10:11], v[10:11], s[58:59] op_sel_hi:[1,0]
	v_pk_mul_f32 v[14:15], v[16:17], s[58:59] op_sel_hi:[1,0]
	v_bfe_u32 v17, v8, 16, 1
	v_pk_mul_f32 v[12:13], v[12:13], s[58:59] op_sel_hi:[1,0]
	v_bfe_u32 v2, v15, 16, 1
	v_bfe_u32 v7, v14, 16, 1
	v_bfe_u32 v16, v9, 16, 1
	v_add3_u32 v8, v8, v17, s85
	v_bfe_u32 v17, v11, 16, 1
	v_add3_u32 v9, v9, v16, s85
	v_add3_u32 v7, v14, v7, s85
	v_add3_u32 v2, v15, v2, s85
	v_bfe_u32 v14, v12, 16, 1
	v_bfe_u32 v15, v13, 16, 1
	v_bfe_u32 v16, v10, 16, 1
	v_add3_u32 v11, v11, v17, s85
	v_lshl_add_u64 v[4:5], s[26:27], 0, v[4:5]
	v_add3_u32 v10, v10, v16, s85
	v_add3_u32 v13, v13, v15, s85
	v_add3_u32 v12, v12, v14, s85
	v_lshrrev_b32_e32 v11, 16, v11
	s_lshl_b32 s42, s65, 1
	v_lshrrev_b32_e32 v12, 16, v12
	v_lshrrev_b32_e32 v13, 16, v13
	v_lshrrev_b32_e32 v10, 16, v10
	v_and_or_b32 v11, v2, s86, v11
	v_lshl_add_u64 v[4:5], v[4:5], 0, s[42:43]
	v_lshlrev_b32_e32 v2, 1, v0
	v_and_or_b32 v10, v7, s86, v10
	v_and_or_b32 v9, v9, s86, v13
	v_and_or_b32 v8, v8, s86, v12
	v_lshl_add_u64 v[4:5], v[4:5], 0, v[2:3]
	flat_store_dwordx4 v[4:5], v[8:11] nt
; #define LAS __attribute__((address_space(3)))
; __device__ __forceinline__ unsigned pk2(float lo, float hi) { return f2bf(lo) | (f2bf(hi) << 16); }
; __device__ __forceinline__ bf16_t* tmap(int mode, int n, bf16_t* d0, bf16_t* d1, int K, float& cs) {
;     ...
;     if (mode == 2) {
;         cs = 0.07216878364870322f * LOG2E;
;         const int hh = n / 192, d = n - hh * 192; int r;
;         if (d < 128) r = hh * 128 + d;
;         else { const int e = d - 128, i = e & 31, hf = e >> 5; r = 1024 + hh * 64 + 8 * (i >> 2) + 4 * hf + (i & 3); }
;         return d0 + (size_t)r * K;
;     }
; __device__ __forceinline__ void transpose_item(const float* W, int K, int N, int mode, const float* kscale, bf16_t* d0, bf16_t* d1, LAS float* scr, int item, int lane) {
;     ...
;     for (int j = 0; j < 4; ++j) { const int n = (lane >> 3) + 8 * j; const LAS float* s = scr + (8 * c) * 33 + n;
;         if (n0 + n < N) { float cs; bf16_t* dst = tmap(mode, n0 + n, d0, d1, K, cs);
;             u32x4 o; o.x = pk2(s[0 * 33] * cs, s[1 * 33] * cs); o.y = pk2(s[2 * 33] * cs, s[3 * 33] * cs); o.z = pk2(s[4 * 33] * cs, s[5 * 33] * cs); o.w = pk2(s[6 * 33] * cs, s[7 * 33] * cs);
;             *(u32x4*)(dst + k0 + 8 * c) = o; } }
.LBB0_483:
	s_or_b64 exec, exec, s[4:5]
	v_add_u32_e32 v2, s67, v74
	v_cmp_gt_i32_e32 vcc, s89, v2
	s_and_saveexec_b64 s[4:5], vcc
	s_cbranch_execz .LBB0_489
	v_mul_hi_i32 v2, v2, s90
	v_lshrrev_b32_e32 v4, 31, v2
	v_ashrrev_i32_e32 v2, 5, v2
	v_add_u32_e32 v2, v2, v4
	v_mul_lo_u32 v4, v2, s91
	v_add3_u32 v5, v6, v4, s66
	v_add_u32_e32 v4, 0xfffc1410, v5
	v_cmp_lt_i32_e32 vcc, s92, v4
	v_lshlrev_b32_e32 v2, 6, v2
	s_and_saveexec_b64 s[40:41], vcc
	s_xor_b64 s[62:63], exec, s[40:41]
	v_add_u32_e32 v4, 0xfffc1390, v5
	v_lshrrev_b32_e32 v4, 3, v4
	v_and_b32_e32 v4, 0x1ffffffc, v4
	v_add3_u32 v4, v46, v2, v4
	s_andn2_saveexec_b64 s[62:63], s[62:63]
	v_sub_u32_e32 v2, v6, v2
	v_add_u32_e32 v2, s66, v2
	v_add_u32_e32 v4, 0xfffc1410, v2
	s_or_b64 exec, exec, s[62:63]
	ds_read2_b32 v[8:9], v40 offset0:16 offset1:49
	ds_read2_b32 v[10:11], v40 offset0:82 offset1:115
	ds_read2_b32 v[14:15], v40 offset0:148 offset1:181
	ds_read2_b32 v[16:17], v40 offset0:214 offset1:247
	v_ashrrev_i32_e32 v5, 31, v4
	v_lshlrev_b64 v[4:5], 10, v[4:5]
	s_waitcnt lgkmcnt(0)
	v_mov_b32_e32 v12, v8
	v_mov_b32_e32 v13, v10
	v_mov_b32_e32 v10, v9
	v_pk_mul_f32 v[8:9], v[10:11], s[58:59] op_sel_hi:[1,0]
	v_mov_b32_e32 v10, v14
	v_mov_b32_e32 v11, v16
	v_mov_b32_e32 v16, v15
	v_pk_mul_f32 v[10:11], v[10:11], s[58:59] op_sel_hi:[1,0]
	v_pk_mul_f32 v[14:15], v[16:17], s[58:59] op_sel_hi:[1,0]
	v_bfe_u32 v17, v8, 16, 1
	v_pk_mul_f32 v[12:13], v[12:13], s[58:59] op_sel_hi:[1,0]
	v_bfe_u32 v2, v15, 16, 1
	v_bfe_u32 v7, v14, 16, 1
	v_bfe_u32 v16, v9, 16, 1
	v_add3_u32 v8, v8, v17, s85
	v_bfe_u32 v17, v11, 16, 1
	v_add3_u32 v9, v9, v16, s85
	v_add3_u32 v7, v14, v7, s85
	v_add3_u32 v2, v15, v2, s85
	v_bfe_u32 v14, v12, 16, 1
	v_bfe_u32 v15, v13, 16, 1
	v_bfe_u32 v16, v10, 16, 1
	v_add3_u32 v11, v11, v17, s85
	v_lshl_add_u64 v[4:5], s[26:27], 0, v[4:5]
	v_add3_u32 v10, v10, v16, s85
	v_add3_u32 v13, v13, v15, s85
	v_add3_u32 v12, v12, v14, s85
	v_lshrrev_b32_e32 v11, 16, v11
	s_lshl_b32 s42, s65, 1
	v_lshrrev_b32_e32 v12, 16, v12
	v_lshrrev_b32_e32 v13, 16, v13
	v_lshrrev_b32_e32 v10, 16, v10
	v_and_or_b32 v11, v2, s86, v11
	v_lshl_add_u64 v[4:5], v[4:5], 0, s[42:43]
	v_lshlrev_b32_e32 v2, 1, v0
	v_and_or_b32 v10, v7, s86, v10
	v_and_or_b32 v9, v9, s86, v13
	v_and_or_b32 v8, v8, s86, v12
	v_lshl_add_u64 v[4:5], v[4:5], 0, v[2:3]
	flat_store_dwordx4 v[4:5], v[8:11] nt
.LBB0_489:
	s_or_b64 exec, exec, s[4:5]
	v_add_u32_e32 v2, s67, v73
	v_cmp_gt_i32_e32 vcc, s89, v2
	s_and_saveexec_b64 s[4:5], vcc
	s_cbranch_execz .LBB0_495
	v_mul_hi_i32 v2, v2, s90
	v_lshrrev_b32_e32 v4, 31, v2
	v_ashrrev_i32_e32 v2, 5, v2
	v_add_u32_e32 v2, v2, v4
	v_mul_lo_u32 v4, v2, s91
	v_add3_u32 v5, v6, v4, s66
	v_add_u32_e32 v4, 0xfffc1418, v5
	v_cmp_lt_i32_e32 vcc, s92, v4
	v_lshlrev_b32_e32 v2, 6, v2
	s_and_saveexec_b64 s[40:41], vcc
	s_xor_b64 s[62:63], exec, s[40:41]
	v_add_u32_e32 v4, 0xfffc1398, v5
	v_lshrrev_b32_e32 v4, 3, v4
	v_and_b32_e32 v4, 0x1ffffffc, v4
	v_add3_u32 v4, v47, v2, v4
	s_andn2_saveexec_b64 s[62:63], s[62:63]
	v_sub_u32_e32 v2, v6, v2
	v_add_u32_e32 v2, s66, v2
	v_add_u32_e32 v4, 0xfffc1418, v2
	s_or_b64 exec, exec, s[62:63]
	ds_read2_b32 v[6:7], v40 offset0:24 offset1:57
	ds_read2_b32 v[8:9], v40 offset0:90 offset1:123
	ds_read2_b32 v[12:13], v40 offset0:156 offset1:189
	ds_read2_b32 v[14:15], v40 offset0:222 offset1:255
	v_ashrrev_i32_e32 v5, 31, v4
	v_lshlrev_b64 v[4:5], 10, v[4:5]
	v_lshl_add_u64 v[10:11], s[26:27], 0, v[4:5]
	s_waitcnt lgkmcnt(0)
	v_mov_b32_e32 v5, v8
	v_mov_b32_e32 v8, v7
	v_mov_b32_e32 v4, v6
	v_pk_mul_f32 v[6:7], v[8:9], s[58:59] op_sel_hi:[1,0]
	v_mov_b32_e32 v9, v14
	v_mov_b32_e32 v14, v13
	v_mov_b32_e32 v8, v12
	v_pk_mul_f32 v[12:13], v[14:15], s[58:59] op_sel_hi:[1,0]
	v_pk_mul_f32 v[8:9], v[8:9], s[58:59] op_sel_hi:[1,0]
	v_bfe_u32 v2, v13, 16, 1
	v_bfe_u32 v14, v12, 16, 1
	v_bfe_u32 v16, v6, 16, 1
	v_pk_mul_f32 v[4:5], v[4:5], s[58:59] op_sel_hi:[1,0]
	v_bfe_u32 v15, v7, 16, 1
	v_add3_u32 v16, v6, v16, s85
	v_add3_u32 v6, v12, v14, s85
	v_add3_u32 v2, v13, v2, s85
	v_bfe_u32 v13, v8, 16, 1
	v_bfe_u32 v14, v9, 16, 1
	v_add3_u32 v15, v7, v15, s85
	v_bfe_u32 v7, v4, 16, 1
	v_bfe_u32 v12, v5, 16, 1
	v_add3_u32 v9, v9, v14, s85
	v_add3_u32 v8, v8, v13, s85
	v_add3_u32 v5, v5, v12, s85
	v_add3_u32 v4, v4, v7, s85
	v_lshrrev_b32_e32 v8, 16, v8
	v_lshrrev_b32_e32 v7, 16, v9
	s_lshl_b32 s42, s65, 1
	v_lshrrev_b32_e32 v4, 16, v4
	v_lshrrev_b32_e32 v5, 16, v5
	v_and_or_b32 v7, v2, s86, v7
	v_and_or_b32 v6, v6, s86, v8
	v_lshl_add_u64 v[8:9], v[10:11], 0, s[42:43]
	v_lshlrev_b32_e32 v2, 1, v0
	v_and_or_b32 v5, v15, s86, v5
	v_and_or_b32 v4, v16, s86, v4
	v_lshl_add_u64 v[8:9], v[8:9], 0, v[2:3]
	flat_store_dwordx4 v[8:9], v[4:7] nt

; #define LAS __attribute__((address_space(3)))
; __device__ __forceinline__ unsigned pk2(float lo, float hi) { return f2bf(lo) | (f2bf(hi) << 16); }
; __device__ __forceinline__ bf16_t* tmap(int mode, int n, bf16_t* d0, bf16_t* d1, int K, float& cs) {
;     ...
;     if (mode == 1) {
;         int r;
;         if (n < 512) r = PC_QLAT + n;
;         else if (n < 768) r = PC_KVLAT + (n - 512);
;         else if (n < 832) r = PC_KPE + (n - 768);
;         else if (n < 1856) { r = PC_FQ + (n - 832); cs = 0.08838834764831845f * LOG2E; }
;         else if (n < 2880) r = PC_FK + (n - 1856);
;         else if (n < 3904) return d1 + (size_t)(n - 2880) * K;
;         else if (n < 3912) r = PC_FLOG + (n - 3904);
;         else r = PC_GATE + (n - 3912);
;         return d0 + (size_t)r * K;
;     }
; __device__ __forceinline__ void transpose_item(const float* W, int K, int N, int mode, const float* kscale, bf16_t* d0, bf16_t* d1, LAS float* scr, int item, int lane) {
;     ...
;     for (int j = 0; j < 4; ++j) { const int n = (lane >> 3) + 8 * j; const LAS float* s = scr + (8 * c) * 33 + n;
;         if (n0 + n < N) { float cs; bf16_t* dst = tmap(mode, n0 + n, d0, d1, K, cs);
;             u32x4 o; o.x = pk2(s[0 * 33] * cs, s[1 * 33] * cs); o.y = pk2(s[2 * 33] * cs, s[3 * 33] * cs); o.z = pk2(s[4 * 33] * cs, s[5 * 33] * cs); o.w = pk2(s[6 * 33] * cs, s[7 * 33] * cs);
;             *(u32x4*)(dst + k0 + 8 * c) = o; } }
.LBB0_596:
	s_or_b64 exec, exec, s[64:65]
	ds_read2_b32 v[4:5], v40 offset1:33
	ds_read2_b32 v[12:13], v40 offset0:66 offset1:99
	ds_read2_b32 v[14:15], v40 offset0:132 offset1:165
	ds_read2_b32 v[16:17], v40 offset0:198 offset1:231
	v_lshlrev_b64 v[6:7], 12, v[6:7]
	v_lshl_add_u64 v[8:9], v[8:9], 0, v[6:7]
	s_waitcnt lgkmcnt(0)
	v_mov_b32_e32 v6, v4
	v_mov_b32_e32 v7, v12
	v_mov_b32_e32 v12, v5
	v_pk_mul_f32 v[4:5], v[2:3], v[12:13] op_sel_hi:[0,1]
	v_mov_b32_e32 v13, v16
	v_mov_b32_e32 v16, v15
	v_mov_b32_e32 v12, v14
	v_pk_mul_f32 v[14:15], v[2:3], v[16:17] op_sel_hi:[0,1]
	v_pk_mul_f32 v[6:7], v[2:3], v[6:7] op_sel_hi:[0,1]
	v_pk_mul_f32 v[12:13], v[2:3], v[12:13] op_sel_hi:[0,1]
	v_bfe_u32 v2, v15, 16, 1
	v_bfe_u32 v17, v4, 16, 1
	v_bfe_u32 v11, v14, 16, 1
	v_bfe_u32 v16, v5, 16, 1
	v_add3_u32 v4, v4, v17, s85
	v_add3_u32 v2, v15, v2, s85
	v_bfe_u32 v15, v7, 16, 1
	v_bfe_u32 v17, v13, 16, 1
	v_add3_u32 v5, v5, v16, s85
	v_add3_u32 v11, v14, v11, s85
	v_bfe_u32 v14, v6, 16, 1
	v_bfe_u32 v16, v12, 16, 1
	v_add3_u32 v13, v13, v17, s85
	v_add3_u32 v7, v7, v15, s85
	v_add3_u32 v12, v12, v16, s85
	v_add3_u32 v6, v6, v14, s85
	v_lshrrev_b32_e32 v15, 16, v7
	v_lshrrev_b32_e32 v7, 16, v13
	v_lshrrev_b32_e32 v14, 16, v6
	v_lshrrev_b32_e32 v6, 16, v12
	v_and_or_b32 v7, v2, s86, v7
	v_lshl_add_u64 v[8:9], s[4:5], 1, v[8:9]
	v_lshlrev_b32_e32 v2, 1, v0
	v_and_or_b32 v6, v11, s86, v6
	v_and_or_b32 v5, v5, s86, v15
	v_and_or_b32 v4, v4, s86, v14
	v_lshl_add_u64 v[8:9], v[8:9], 0, v[2:3]
	flat_store_dwordx4 v[8:9], v[4:7] nt

; #define LAS __attribute__((address_space(3)))
; __device__ __forceinline__ unsigned pk2(float lo, float hi) { return f2bf(lo) | (f2bf(hi) << 16); }
; __device__ __forceinline__ bf16_t* tmap(int mode, int n, bf16_t* d0, bf16_t* d1, int K, float& cs) {
;     ...
;     if (mode == 1) {
;         int r;
;         if (n < 512) r = PC_QLAT + n;
;         else if (n < 768) r = PC_KVLAT + (n - 512);
;         else if (n < 832) r = PC_KPE + (n - 768);
;         else if (n < 1856) { r = PC_FQ + (n - 832); cs = 0.08838834764831845f * LOG2E; }
;         else if (n < 2880) r = PC_FK + (n - 1856);
;         else if (n < 3904) return d1 + (size_t)(n - 2880) * K;
;         else if (n < 3912) r = PC_FLOG + (n - 3904);
;         else r = PC_GATE + (n - 3912);
;         return d0 + (size_t)r * K;
;     }
; __device__ __forceinline__ void transpose_item(const float* W, int K, int N, int mode, const float* kscale, bf16_t* d0, bf16_t* d1, LAS float* scr, int item, int lane) {
;     ...
;     for (int j = 0; j < 4; ++j) { const int n = (lane >> 3) + 8 * j; const LAS float* s = scr + (8 * c) * 33 + n;
;         if (n0 + n < N) { float cs; bf16_t* dst = tmap(mode, n0 + n, d0, d1, K, cs);
;             u32x4 o; o.x = pk2(s[0 * 33] * cs, s[1 * 33] * cs); o.y = pk2(s[2 * 33] * cs, s[3 * 33] * cs); o.z = pk2(s[4 * 33] * cs, s[5 * 33] * cs); o.w = pk2(s[6 * 33] * cs, s[7 * 33] * cs);
;             *(u32x4*)(dst + k0 + 8 * c) = o; } }
.LBB0_628:
	s_or_b64 exec, exec, s[64:65]
	ds_read2_b32 v[4:5], v40 offset0:8 offset1:41
	ds_read2_b32 v[12:13], v40 offset0:74 offset1:107
	ds_read2_b32 v[14:15], v40 offset0:140 offset1:173
	ds_read2_b32 v[16:17], v40 offset0:206 offset1:239
	v_lshlrev_b64 v[6:7], 12, v[6:7]
	v_lshl_add_u64 v[8:9], v[8:9], 0, v[6:7]
	s_waitcnt lgkmcnt(0)
	v_mov_b32_e32 v6, v4
	v_mov_b32_e32 v7, v12
	v_mov_b32_e32 v12, v5
	v_pk_mul_f32 v[4:5], v[2:3], v[12:13] op_sel_hi:[0,1]
	v_mov_b32_e32 v13, v16
	v_mov_b32_e32 v16, v15
	v_mov_b32_e32 v12, v14
	v_pk_mul_f32 v[14:15], v[2:3], v[16:17] op_sel_hi:[0,1]
	v_pk_mul_f32 v[6:7], v[2:3], v[6:7] op_sel_hi:[0,1]
	v_pk_mul_f32 v[12:13], v[2:3], v[12:13] op_sel_hi:[0,1]
	v_bfe_u32 v2, v15, 16, 1
	v_bfe_u32 v17, v4, 16, 1
	v_bfe_u32 v11, v14, 16, 1
	v_bfe_u32 v16, v5, 16, 1
	v_add3_u32 v4, v4, v17, s85
	v_add3_u32 v2, v15, v2, s85
	v_bfe_u32 v15, v7, 16, 1
	v_bfe_u32 v17, v13, 16, 1
	v_add3_u32 v5, v5, v16, s85
	v_add3_u32 v11, v14, v11, s85
	v_bfe_u32 v14, v6, 16, 1
	v_bfe_u32 v16, v12, 16, 1
	v_add3_u32 v13, v13, v17, s85
	v_add3_u32 v7, v7, v15, s85
	v_add3_u32 v12, v12, v16, s85
	v_add3_u32 v6, v6, v14, s85
	v_lshrrev_b32_e32 v15, 16, v7
	v_lshrrev_b32_e32 v7, 16, v13
	v_lshrrev_b32_e32 v14, 16, v6
	v_lshrrev_b32_e32 v6, 16, v12
	v_and_or_b32 v7, v2, s86, v7
	v_lshl_add_u64 v[8:9], s[4:5], 1, v[8:9]
	v_lshlrev_b32_e32 v2, 1, v0
	v_and_or_b32 v6, v11, s86, v6
	v_and_or_b32 v5, v5, s86, v15
	v_and_or_b32 v4, v4, s86, v14
	v_lshl_add_u64 v[8:9], v[8:9], 0, v[2:3]
	flat_store_dwordx4 v[8:9], v[4:7] nt

; #define LAS __attribute__((address_space(3)))
; __device__ __forceinline__ unsigned pk2(float lo, float hi) { return f2bf(lo) | (f2bf(hi) << 16); }
; __device__ __forceinline__ bf16_t* tmap(int mode, int n, bf16_t* d0, bf16_t* d1, int K, float& cs) {
;     ...
;     if (mode == 1) {
;         int r;
;         if (n < 512) r = PC_QLAT + n;
;         else if (n < 768) r = PC_KVLAT + (n - 512);
;         else if (n < 832) r = PC_KPE + (n - 768);
;         else if (n < 1856) { r = PC_FQ + (n - 832); cs = 0.08838834764831845f * LOG2E; }
;         else if (n < 2880) r = PC_FK + (n - 1856);
;         else if (n < 3904) return d1 + (size_t)(n - 2880) * K;
;         else if (n < 3912) r = PC_FLOG + (n - 3904);
;         else r = PC_GATE + (n - 3912);
;         return d0 + (size_t)r * K;
;     }
; __device__ __forceinline__ void transpose_item(const float* W, int K, int N, int mode, const float* kscale, bf16_t* d0, bf16_t* d1, LAS float* scr, int item, int lane) {
;     ...
;     for (int j = 0; j < 4; ++j) { const int n = (lane >> 3) + 8 * j; const LAS float* s = scr + (8 * c) * 33 + n;
;         if (n0 + n < N) { float cs; bf16_t* dst = tmap(mode, n0 + n, d0, d1, K, cs);
;             u32x4 o; o.x = pk2(s[0 * 33] * cs, s[1 * 33] * cs); o.y = pk2(s[2 * 33] * cs, s[3 * 33] * cs); o.z = pk2(s[4 * 33] * cs, s[5 * 33] * cs); o.w = pk2(s[6 * 33] * cs, s[7 * 33] * cs);
;             *(u32x4*)(dst + k0 + 8 * c) = o; } }
.LBB0_660:
	s_or_b64 exec, exec, s[64:65]
	ds_read2_b32 v[4:5], v40 offset0:16 offset1:49
	ds_read2_b32 v[12:13], v40 offset0:82 offset1:115
	ds_read2_b32 v[14:15], v40 offset0:148 offset1:181
	ds_read2_b32 v[16:17], v40 offset0:214 offset1:247
	v_lshlrev_b64 v[6:7], 12, v[6:7]
	v_lshl_add_u64 v[8:9], v[8:9], 0, v[6:7]
	s_waitcnt lgkmcnt(0)
	v_mov_b32_e32 v6, v4
	v_mov_b32_e32 v7, v12
	v_mov_b32_e32 v12, v5
	v_pk_mul_f32 v[4:5], v[2:3], v[12:13] op_sel_hi:[0,1]
	v_mov_b32_e32 v13, v16
	v_mov_b32_e32 v16, v15
	v_mov_b32_e32 v12, v14
	v_pk_mul_f32 v[14:15], v[2:3], v[16:17] op_sel_hi:[0,1]
	v_pk_mul_f32 v[6:7], v[2:3], v[6:7] op_sel_hi:[0,1]
	v_pk_mul_f32 v[12:13], v[2:3], v[12:13] op_sel_hi:[0,1]
	v_bfe_u32 v2, v15, 16, 1
	v_bfe_u32 v17, v4, 16, 1
	v_bfe_u32 v11, v14, 16, 1
	v_bfe_u32 v16, v5, 16, 1
	v_add3_u32 v4, v4, v17, s85
	v_add3_u32 v2, v15, v2, s85
	v_bfe_u32 v15, v7, 16, 1
	v_bfe_u32 v17, v13, 16, 1
	v_add3_u32 v5, v5, v16, s85
	v_add3_u32 v11, v14, v11, s85
	v_bfe_u32 v14, v6, 16, 1
	v_bfe_u32 v16, v12, 16, 1
	v_add3_u32 v13, v13, v17, s85
	v_add3_u32 v7, v7, v15, s85
	v_add3_u32 v12, v12, v16, s85
	v_add3_u32 v6, v6, v14, s85
	v_lshrrev_b32_e32 v15, 16, v7
	v_lshrrev_b32_e32 v7, 16, v13
	v_lshrrev_b32_e32 v14, 16, v6
	v_lshrrev_b32_e32 v6, 16, v12
	v_and_or_b32 v7, v2, s86, v7
	v_lshl_add_u64 v[8:9], s[4:5], 1, v[8:9]
	v_lshlrev_b32_e32 v2, 1, v0
	v_and_or_b32 v6, v11, s86, v6
	v_and_or_b32 v5, v5, s86, v15
	v_and_or_b32 v4, v4, s86, v14
	v_lshl_add_u64 v[8:9], v[8:9], 0, v[2:3]
	flat_store_dwordx4 v[8:9], v[4:7] nt

; __global__ void __launch_bounds__(512, 2) mega_fwd(Args a) {
;     ...
;         { u32x4* z = (u32x4*)(Win_t + (size_t)PC_END * 2048); const int nz = (NPROJ - PC_END) * 2048 / 8;
;           for (int i = bx * 512 + tid; i < nz; i += G * 512) z[i] = (u32x4){0u, 0u, 0u, 0u}; }
.LBB0_694:
	v_add_u32_e32 v6, s8, v6
	v_cmp_lt_i32_e32 vcc, s9, v6
	flat_store_dwordx4 v[4:5], v[0:3] nt
	s_or_b64 s[12:13], vcc, s[12:13]
	v_lshl_add_u64 v[4:5], v[4:5], 0, s[10:11]
	s_andn2_b64 exec, exec, s[12:13]
	s_cbranch_execnz .LBB0_694
